# adds: write-through (sc1) on the fused-norm residual-stream stores so their write-back overlaps the epilogue instead of the barrier
# baseline (speedup 1.0000x reference)
; #define LAS __attribute__((address_space(3)))
;     __device__ __forceinline__ HT hload(unsigned eoff) const { const u32x2 a = *(const u32x2*)((const char*)hi + eoff * 2u); const u32x2 b = *(const u32x2*)((const char*)lo + eoff * 2u); return (u32x4){a.x, a.y, b.x, b.y}; }
;     __device__ __forceinline__ void fused(f32x4 (&acc)[2][2][4][2], const Unit& u, int wr, int wc, int fr, int fq, LAS unsigned char* lds, int wid, int lane) const {
;     ...
;         const f32x4 g1q = *(const f32x4*)(g1 + u.pn * BM + 4 * lane);
; #pragma unroll
;         for (int ai = 0; ai < 2; ++ai) {
;             if (ai == 1) {
; #pragma unroll
;             for (int m = 0; m < 4; ++m)
; #pragma unroll
;                 for (int bj = 0; bj < 2; ++bj)
; #pragma unroll
;                     for (int n = 0; n < 2; ++n) { const int r = wr * 64 + m * 16 + fr, c16 = 32 * bj + 8 * wc + 4 * n + fq;
;                         *(LAS f32x4*)(lds + r * 1024 + ((c16 ^ (r & 15)) << 4)) = acc[1][bj][m][n]; }
;             }
;             asm volatile("s_waitcnt lgkmcnt(0)" ::: "memory"); __builtin_amdgcn_s_barrier(); asm volatile("" ::: "memory");
;             if (ai == 0) {
;                 asm volatile("" :: "v"(H[0]), "v"(H[1]), "v"(H[2]), "v"(H[3]), "v"(H[4]), "v"(H[5]), "v"(H[6]), "v"(H[7]), "v"(H[8]), "v"(H[9]), "v"(H[10]), "v"(H[11]), "v"(H[12]), "v"(H[13]), "v"(H[14]), "v"(H[15]));
; #pragma unroll
;                 for (int j = 0; j < 16; ++j) H2[j] = hload(rbase + (unsigned)((HALF + j) * D));
;             }
;             float sqt = 0.f;
;     ...
;             if (ai == 0) EN_ROWS(4); else EN_ROWS(8);
.LBB0_323:
	s_or_b64 exec, exec, s[20:21]
	v_readlane_b32 s16, v254, 37
	v_readlane_b32 s17, v254, 38
	s_lshl_b64 s[16:17], s[16:17], 2
	s_add_u32 s16, s14, s16
	s_addc_u32 s17, s15, s17
	s_ashr_i32 s19, s18, 31
	s_lshl_b64 s[14:15], s[18:19], 2
	s_add_u32 s14, s16, s14
	s_addc_u32 s15, s17, s15
	v_lshlrev_b32_e32 v4, 2, v3
	v_lshl_add_u64 v[2:3], s[14:15], 0, v[4:5]
	s_movk_i32 s14, 0x2000
	v_add_co_u32_e32 v2, vcc, s14, v2
	v_add_u32_e32 v4, 0x82000, v154
	s_nop 0
	v_addc_co_u32_e32 v3, vcc, 0, v3, vcc
	global_load_dwordx4 v[70:73], v[2:3], off
	v_add_u32_e32 v2, 0x80000, v154
	v_add_u32_e32 v3, 0x81000, v154
	s_waitcnt lgkmcnt(0)
	s_barrier
	s_waitcnt vmcnt(0)
	v_add_u32_e32 v76, 0x83000, v154
	global_load_dwordx2 v[122:123], v2, s[4:5]
	global_load_dwordx2 v[120:121], v3, s[4:5]
	global_load_dwordx2 v[118:119], v4, s[4:5]
	global_load_dwordx2 v[116:117], v76, s[4:5]
	v_add_u32_e32 v2, 0x84000, v154
	v_add_u32_e32 v3, 0x85000, v154
	v_add_u32_e32 v4, 0x86000, v154
	v_add_u32_e32 v76, 0x87000, v154
	global_load_dwordx2 v[114:115], v2, s[4:5]
	global_load_dwordx2 v[112:113], v3, s[4:5]
	global_load_dwordx2 v[110:111], v4, s[4:5]
	global_load_dwordx2 v[108:109], v76, s[4:5]
	v_add_u32_e32 v2, 0x88000, v154
	v_add_u32_e32 v3, 0x89000, v154
	v_add_u32_e32 v4, 0x8a000, v154
	v_add_u32_e32 v76, 0x8b000, v154
	global_load_dwordx2 v[106:107], v2, s[4:5]
	global_load_dwordx2 v[104:105], v3, s[4:5]
	global_load_dwordx2 v[102:103], v4, s[4:5]
	global_load_dwordx2 v[100:101], v76, s[4:5]
	v_add_u32_e32 v2, 0x8c000, v154
	v_add_u32_e32 v3, 0x8d000, v154
	v_add_u32_e32 v4, 0x8e000, v154
	v_add_u32_e32 v76, 0x8f000, v154
	global_load_dwordx2 v[98:99], v2, s[4:5]
	global_load_dwordx2 v[96:97], v3, s[4:5]
	global_load_dwordx2 v[94:95], v4, s[4:5]
	s_nop 0
	global_load_dwordx2 v[2:3], v76, s[4:5]
	s_lshl_b32 s15, s44, 6
	s_lshl_b32 s14, s44, 14
	s_add_i32 s18, s15, 0
	s_add_i32 s14, s14, 0
	v_lshlrev_b32_e32 v168, 4, v156
	s_add_i32 s18, s18, 0x21400
	v_add_u32_e32 v4, s14, v168
	v_mov_b32_e32 v76, s18
	ds_read_b128 v[170:173], v4
	ds_read_b128 v[78:81], v76
	s_add_i32 s15, s14, 0x400
	v_xor_b32_e32 v76, 16, v168
	v_add_u32_e32 v162, s15, v76
	s_add_i32 s15, s14, 0x800
	v_xor_b32_e32 v76, 32, v168
	v_add_u32_e32 v163, s15, v76
	s_addk_i32 s14, 0xc00
	v_xor_b32_e32 v76, 48, v168
	v_add_u32_e32 v164, s14, v76
	ds_read_b128 v[86:89], v162
	ds_read_b128 v[90:93], v163
	ds_read_b128 v[82:85], v164
	v_lshlrev_b32_e32 v166, 16, v74
	v_and_b32_e32 v167, 0xffff0000, v74
	v_lshlrev_b32_e32 v74, 16, v75
	v_and_b32_e32 v75, 0xffff0000, v75
	s_waitcnt lgkmcnt(4)
	v_pk_mul_f32 v[76:77], v[72:73], v[172:173]
	v_pk_mul_f32 v[170:171], v[70:71], v[170:171]
	s_cmp_lg_u64 s[8:9], 0
	s_waitcnt lgkmcnt(3)
	v_pk_fma_f32 v[76:77], v[76:77], v[78:79], v[74:75] op_sel_hi:[1,0,1]
	s_cselect_b64 s[14:15], -1, 0
	s_cmp_eq_u64 s[8:9], 0
	v_pk_fma_f32 v[74:75], v[170:171], v[78:79], v[166:167] op_sel_hi:[1,0,1]
	s_cbranch_scc1 .LBB0_437
	v_lshlrev_b32_e32 v155, 2, v157
	global_store_dwordx4 v155, v[74:77], s[8:9] sc1
	s_cbranch_execnz .LBB0_326
.LBB0_325:
	v_mov_b32_e32 v155, v5
	v_lshl_add_u64 v[154:155], s[4:5], 0, v[154:155]
	v_cvt_pk_bf16_f32 v166, v74, v75
	v_cvt_pk_bf16_f32 v167, v76, v77
	global_store_dwordx2 v[154:155], v[166:167], off sc1
.LBB0_326:
	v_lshlrev_b32_e32 v154, 16, v152
	v_and_b32_e32 v155, 0xffff0000, v152
	v_lshlrev_b32_e32 v152, 16, v153
	v_and_b32_e32 v153, 0xffff0000, v153
	s_waitcnt lgkmcnt(2)
	v_pk_mul_f32 v[88:89], v[72:73], v[88:89]
	v_pk_mul_f32 v[86:87], v[70:71], v[86:87]
	v_pk_fma_f32 v[88:89], v[88:89], v[78:79], v[152:153] op_sel:[0,1,0]
	v_pk_fma_f32 v[86:87], v[86:87], v[78:79], v[154:155] op_sel:[0,1,0]
	v_cndmask_b32_e64 v78, 0, 1, s[14:15]
	v_cmp_ne_u32_e64 s[42:43], 1, v78
	s_andn2_b64 vcc, exec, s[14:15]
	v_add_u32_e32 v78, 0x800, v157
	s_cbranch_vccnz .LBB0_438
	v_lshlrev_b32_e32 v79, 2, v78
	global_store_dwordx4 v79, v[86:89], s[8:9] sc1
	s_cbranch_execnz .LBB0_329
.LBB0_328:
	v_cvt_pk_bf16_f32 v152, v86, v87
	v_cvt_pk_bf16_f32 v153, v88, v89
	v_lshlrev_b32_e32 v78, 1, v78
	global_store_dwordx2 v78, v[152:153], s[4:5] sc1
.LBB0_329:
	v_lshlrev_b32_e32 v78, 16, v150
	v_and_b32_e32 v79, 0xffff0000, v150
	v_lshlrev_b32_e32 v150, 16, v151
	v_and_b32_e32 v151, 0xffff0000, v151
	s_waitcnt lgkmcnt(1)
	v_pk_mul_f32 v[92:93], v[72:73], v[92:93]
	v_pk_mul_f32 v[90:91], v[70:71], v[90:91]
	v_pk_fma_f32 v[92:93], v[92:93], v[80:81], v[150:151] op_sel_hi:[1,0,1]
	v_pk_fma_f32 v[90:91], v[90:91], v[80:81], v[78:79] op_sel_hi:[1,0,1]
	s_and_b64 vcc, exec, s[42:43]
	v_add_u32_e32 v78, 0x1000, v157
	s_cbranch_vccnz .LBB0_439
	v_lshlrev_b32_e32 v79, 2, v78
	global_store_dwordx4 v79, v[90:93], s[8:9] sc1
	s_cbranch_execnz .LBB0_332
.LBB0_331:
	v_cvt_pk_bf16_f32 v150, v90, v91
	v_cvt_pk_bf16_f32 v151, v92, v93
	v_lshlrev_b32_e32 v78, 1, v78
	global_store_dwordx2 v78, v[150:151], s[4:5] sc1
.LBB0_332:
	v_lshlrev_b32_e32 v78, 16, v148
	v_and_b32_e32 v79, 0xffff0000, v148
	v_lshlrev_b32_e32 v148, 16, v149
	v_and_b32_e32 v149, 0xffff0000, v149
	s_waitcnt lgkmcnt(0)
	v_pk_mul_f32 v[84:85], v[72:73], v[84:85]
	v_pk_mul_f32 v[82:83], v[70:71], v[82:83]
	v_mov_b32_e32 v150, v81
	v_pk_fma_f32 v[80:81], v[84:85], v[150:151], v[148:149] op_sel_hi:[1,0,1]
	v_pk_fma_f32 v[78:79], v[82:83], v[150:151], v[78:79] op_sel_hi:[1,0,1]
	s_and_b64 vcc, exec, s[42:43]
	v_add_u32_e32 v82, 0x1800, v157
	s_cbranch_vccnz .LBB0_440
	v_lshlrev_b32_e32 v83, 2, v82
	global_store_dwordx4 v83, v[78:81], s[8:9] sc1
	s_lshl_b32 s20, s44, 4
	s_cbranch_execnz .LBB0_335
.LBB0_334:
	v_cvt_pk_bf16_f32 v84, v78, v79
	v_cvt_pk_bf16_f32 v85, v80, v81
	v_lshlrev_b32_e32 v82, 1, v82
	global_store_dwordx2 v82, v[84:85], s[4:5] sc1
;     __device__ __forceinline__ void fused(f32x4 (&acc)[2][2][4][2], const Unit& u, int wr, int wc, int fr, int fq, LAS unsigned char* lds, int wid, int lane) const {
;     ...
;             }
;             float sqt = 0.f;
;     ...
;             if (ai == 0) EN_ROWS(4); else EN_ROWS(8);
;     ...
;             if (lane < 16) st2[(size_t)(u.pm * BM + ai * HALF + 16 * wid + lane) * 8 + u.pn] = sqt;
.LBB0_335:
	v_mul_f32_e32 v79, v79, v79
	v_fmac_f32_e32 v79, v78, v78
	v_mul_f32_e32 v78, v81, v81
	v_fmac_f32_e32 v78, v80, v80
	v_mul_f32_e32 v75, v75, v75
	v_add_f32_e32 v78, v79, v78
	v_mul_f32_e32 v79, v91, v91
	v_mul_f32_e32 v80, v93, v93
	v_fmac_f32_e32 v75, v74, v74
	v_mul_f32_e32 v74, v77, v77
	v_fmac_f32_e32 v79, v90, v90
	v_fmac_f32_e32 v80, v92, v92
	v_fmac_f32_e32 v74, v76, v76
	v_add_f32_e32 v79, v79, v80
	v_mul_f32_e32 v80, v87, v87
	v_mul_f32_e32 v81, v89, v89
	v_add_f32_e32 v74, v75, v74
	v_fmac_f32_e32 v80, v86, v86
	v_fmac_f32_e32 v81, v88, v88
	v_add_f32_dpp v74, v74, v74 quad_perm:[1,0,3,2] row_mask:0xf bank_mask:0xf bound_ctrl:1
	v_add_f32_e32 v80, v80, v81
	v_add_f32_dpp v76, v79, v79 quad_perm:[1,0,3,2] row_mask:0xf bank_mask:0xf bound_ctrl:1
	v_add_f32_dpp v74, v74, v74 quad_perm:[2,3,0,1] row_mask:0xf bank_mask:0xf bound_ctrl:1
	v_add_f32_dpp v75, v80, v80 quad_perm:[1,0,3,2] row_mask:0xf bank_mask:0xf bound_ctrl:1
	v_add_f32_dpp v77, v78, v78 quad_perm:[1,0,3,2] row_mask:0xf bank_mask:0xf bound_ctrl:1
	v_add_f32_dpp v74, v74, v74 row_half_mirror row_mask:0xf bank_mask:0xf bound_ctrl:1
	v_add_f32_dpp v75, v75, v75 quad_perm:[2,3,0,1] row_mask:0xf bank_mask:0xf bound_ctrl:1
	v_add_f32_dpp v76, v76, v76 quad_perm:[2,3,0,1] row_mask:0xf bank_mask:0xf bound_ctrl:1
	v_add_f32_dpp v74, v74, v74 row_mirror row_mask:0xf bank_mask:0xf bound_ctrl:1
	v_add_f32_dpp v75, v75, v75 row_half_mirror row_mask:0xf bank_mask:0xf bound_ctrl:1
	v_mov_b32_e32 v78, v74
	s_nop 1
	v_permlane16_swap_b32_e32 v74, v78
	v_add_f32_dpp v75, v75, v75 row_mirror row_mask:0xf bank_mask:0xf bound_ctrl:1
	v_add_f32_dpp v76, v76, v76 row_half_mirror row_mask:0xf bank_mask:0xf bound_ctrl:1
	v_add_f32_e32 v152, v74, v78
	v_mov_b32_e32 v74, v75
	s_or_b32 s14, s20, 4
	v_add_f32_dpp v77, v77, v77 quad_perm:[2,3,0,1] row_mask:0xf bank_mask:0xf bound_ctrl:1
	v_add_f32_dpp v76, v76, v76 row_mirror row_mask:0xf bank_mask:0xf bound_ctrl:1
	v_permlane16_swap_b32_e32 v75, v74
	s_lshl_b32 s15, s14, 10
	s_lshl_b32 s14, s14, 2
	v_add_f32_dpp v77, v77, v77 row_half_mirror row_mask:0xf bank_mask:0xf bound_ctrl:1
	v_add_f32_e32 v153, v75, v74
	v_mov_b32_e32 v74, v76
	s_add_i32 s17, s14, 0
	s_lshl_b32 s14, s20, 10
	v_add_f32_dpp v77, v77, v77 row_mirror row_mask:0xf bank_mask:0xf bound_ctrl:1
	v_permlane16_swap_b32_e32 v76, v74
	s_add_i32 s21, s14, 0
	v_add_f32_e32 v154, v76, v74
	v_mov_b32_e32 v74, v77
	s_add_i32 s14, s21, 0x1400
	v_xor_b32_e32 v82, 0x50, v168
	v_permlane16_swap_b32_e32 v77, v74
	v_add_u32_e32 v149, s14, v82
	s_add_i32 s14, s21, 0x1800
	v_xor_b32_e32 v82, 0x60, v168
	v_add_f32_e32 v155, v77, v74
	s_add_i32 s15, s15, 0
	v_xor_b32_e32 v74, 64, v168
	s_add_i32 s17, s17, 0x21400
	v_add_u32_e32 v150, s14, v82
	s_add_i32 s14, s21, 0x1c00
	v_xor_b32_e32 v82, 0x70, v168
	v_add_u32_e32 v148, s15, v74
	v_mov_b32_e32 v78, s17
	v_add_u32_e32 v151, s14, v82
	ds_read_b128 v[74:77], v148
	ds_read_b128 v[78:81], v78
	ds_read_b128 v[86:89], v149
	ds_read_b128 v[90:93], v150
	ds_read_b128 v[82:85], v151
	v_mov_b32_e32 v165, v152
	v_mov_b32_e32 v166, v153
	v_mov_b32_e32 v167, v154
	v_mov_b32_e32 v169, v155
	v_permlane32_swap_b32_e32 v152, v165
	v_permlane32_swap_b32_e32 v153, v166
	v_permlane32_swap_b32_e32 v154, v167
	v_permlane32_swap_b32_e32 v155, v169
	v_lshlrev_b32_e32 v170, 16, v146
	v_and_b32_e32 v171, 0xffff0000, v146
	v_lshlrev_b32_e32 v146, 16, v147
	v_and_b32_e32 v147, 0xffff0000, v147
	s_waitcnt lgkmcnt(4)
	v_pk_mul_f32 v[76:77], v[72:73], v[76:77]
	v_pk_mul_f32 v[74:75], v[70:71], v[74:75]
	s_waitcnt lgkmcnt(3)
	v_pk_fma_f32 v[76:77], v[76:77], v[78:79], v[146:147] op_sel_hi:[1,0,1]
	v_pk_fma_f32 v[74:75], v[74:75], v[78:79], v[170:171] op_sel_hi:[1,0,1]
	s_and_b64 vcc, exec, s[42:43]
	v_add_u32_e32 v146, 0x2000, v157
	s_cbranch_vccnz .LBB0_441
	v_lshlrev_b32_e32 v147, 2, v146
	global_store_dwordx4 v147, v[74:77], s[8:9] sc1
	s_cbranch_execnz .LBB0_338
.LBB0_337:
	v_cvt_pk_bf16_f32 v170, v74, v75
	v_cvt_pk_bf16_f32 v171, v76, v77
	v_lshlrev_b32_e32 v146, 1, v146
	global_store_dwordx2 v146, v[170:171], s[4:5] sc1
.LBB0_338:
	v_lshlrev_b32_e32 v146, 16, v144
	v_and_b32_e32 v147, 0xffff0000, v144
	v_lshlrev_b32_e32 v144, 16, v145
	v_and_b32_e32 v145, 0xffff0000, v145
	s_waitcnt lgkmcnt(2)
	v_pk_mul_f32 v[88:89], v[72:73], v[88:89]
	v_pk_mul_f32 v[86:87], v[70:71], v[86:87]
	v_pk_fma_f32 v[88:89], v[88:89], v[78:79], v[144:145] op_sel:[0,1,0]
	v_pk_fma_f32 v[86:87], v[86:87], v[78:79], v[146:147] op_sel:[0,1,0]
	s_and_b64 vcc, exec, s[42:43]
	v_add_u32_e32 v78, 0x2800, v157
	s_cbranch_vccnz .LBB0_442
	v_lshlrev_b32_e32 v79, 2, v78
	global_store_dwordx4 v79, v[86:89], s[8:9] sc1
	s_cbranch_execnz .LBB0_341
.LBB0_340:
	v_cvt_pk_bf16_f32 v144, v86, v87
	v_cvt_pk_bf16_f32 v145, v88, v89
	v_lshlrev_b32_e32 v78, 1, v78
	global_store_dwordx2 v78, v[144:145], s[4:5] sc1
.LBB0_341:
	v_lshlrev_b32_e32 v78, 16, v142
	v_and_b32_e32 v79, 0xffff0000, v142
	v_lshlrev_b32_e32 v142, 16, v143
	v_and_b32_e32 v143, 0xffff0000, v143
	s_waitcnt lgkmcnt(1)
	v_pk_mul_f32 v[92:93], v[72:73], v[92:93]
	v_pk_mul_f32 v[90:91], v[70:71], v[90:91]
	v_pk_fma_f32 v[92:93], v[92:93], v[80:81], v[142:143] op_sel_hi:[1,0,1]
	v_pk_fma_f32 v[90:91], v[90:91], v[80:81], v[78:79] op_sel_hi:[1,0,1]
	s_and_b64 vcc, exec, s[42:43]
	v_add_u32_e32 v78, 0x3000, v157
	s_cbranch_vccnz .LBB0_443
	v_lshlrev_b32_e32 v79, 2, v78
	global_store_dwordx4 v79, v[90:93], s[8:9] sc1
	s_cbranch_execnz .LBB0_344
.LBB0_343:
	v_cvt_pk_bf16_f32 v142, v90, v91
	v_cvt_pk_bf16_f32 v143, v92, v93
	v_lshlrev_b32_e32 v78, 1, v78
	global_store_dwordx2 v78, v[142:143], s[4:5] sc1
.LBB0_344:
	v_lshlrev_b32_e32 v78, 16, v140
	v_and_b32_e32 v79, 0xffff0000, v140
	v_lshlrev_b32_e32 v140, 16, v141
	v_and_b32_e32 v141, 0xffff0000, v141
	s_waitcnt lgkmcnt(0)
	v_pk_mul_f32 v[84:85], v[72:73], v[84:85]
	v_pk_mul_f32 v[82:83], v[70:71], v[82:83]
	v_mov_b32_e32 v142, v81
	v_pk_fma_f32 v[80:81], v[84:85], v[142:143], v[140:141] op_sel_hi:[1,0,1]
	v_pk_fma_f32 v[78:79], v[82:83], v[142:143], v[78:79] op_sel_hi:[1,0,1]
	s_and_b64 vcc, exec, s[42:43]
	v_add_u32_e32 v82, 0x3800, v157
	s_cbranch_vccnz .LBB0_444
	v_lshlrev_b32_e32 v83, 2, v82
	global_store_dwordx4 v83, v[78:81], s[8:9] sc1
	s_cbranch_execnz .LBB0_347

;     __device__ __forceinline__ void fused(f32x4 (&acc)[2][2][4][2], const Unit& u, int wr, int wc, int fr, int fq, LAS unsigned char* lds, int wid, int lane) const {
;     ...
;             if (ai == 0) EN_ROWS(4); else EN_ROWS(8);
.LBB0_347:
	s_nop 0
	v_mul_f32_e32 v79, v79, v79
	v_fmac_f32_e32 v79, v78, v78
	v_mul_f32_e32 v78, v81, v81
	v_fmac_f32_e32 v78, v80, v80
	v_mul_f32_e32 v75, v75, v75
	v_add_f32_e32 v78, v79, v78
	v_mul_f32_e32 v79, v91, v91
	v_mul_f32_e32 v80, v93, v93
	v_fmac_f32_e32 v75, v74, v74
	v_mul_f32_e32 v74, v77, v77
	v_fmac_f32_e32 v79, v90, v90
	v_fmac_f32_e32 v80, v92, v92
	v_fmac_f32_e32 v74, v76, v76
	v_add_f32_e32 v79, v79, v80
	v_mul_f32_e32 v80, v87, v87
	v_mul_f32_e32 v81, v89, v89
	v_add_f32_e32 v74, v75, v74
	v_fmac_f32_e32 v80, v86, v86
	v_fmac_f32_e32 v81, v88, v88
	v_add_f32_dpp v74, v74, v74 quad_perm:[1,0,3,2] row_mask:0xf bank_mask:0xf bound_ctrl:1
	v_add_f32_e32 v80, v80, v81
	v_add_f32_dpp v76, v79, v79 quad_perm:[1,0,3,2] row_mask:0xf bank_mask:0xf bound_ctrl:1
	v_add_f32_dpp v74, v74, v74 quad_perm:[2,3,0,1] row_mask:0xf bank_mask:0xf bound_ctrl:1
	v_add_f32_dpp v75, v80, v80 quad_perm:[1,0,3,2] row_mask:0xf bank_mask:0xf bound_ctrl:1
	v_add_f32_dpp v77, v78, v78 quad_perm:[1,0,3,2] row_mask:0xf bank_mask:0xf bound_ctrl:1
	v_add_f32_dpp v74, v74, v74 row_half_mirror row_mask:0xf bank_mask:0xf bound_ctrl:1
	v_add_f32_dpp v75, v75, v75 quad_perm:[2,3,0,1] row_mask:0xf bank_mask:0xf bound_ctrl:1
	v_add_f32_dpp v76, v76, v76 quad_perm:[2,3,0,1] row_mask:0xf bank_mask:0xf bound_ctrl:1
	v_add_f32_dpp v74, v74, v74 row_mirror row_mask:0xf bank_mask:0xf bound_ctrl:1
	v_add_f32_dpp v75, v75, v75 row_half_mirror row_mask:0xf bank_mask:0xf bound_ctrl:1
	v_mov_b32_e32 v78, v74
	s_nop 1
	v_permlane16_swap_b32_e32 v74, v78
	v_add_f32_dpp v75, v75, v75 row_mirror row_mask:0xf bank_mask:0xf bound_ctrl:1
	v_add_f32_dpp v76, v76, v76 row_half_mirror row_mask:0xf bank_mask:0xf bound_ctrl:1
	v_add_f32_e32 v144, v74, v78
	v_mov_b32_e32 v74, v75
	v_add_f32_dpp v77, v77, v77 quad_perm:[2,3,0,1] row_mask:0xf bank_mask:0xf bound_ctrl:1
	v_add_f32_dpp v76, v76, v76 row_mirror row_mask:0xf bank_mask:0xf bound_ctrl:1
	v_permlane16_swap_b32_e32 v75, v74
	v_add_f32_dpp v77, v77, v77 row_half_mirror row_mask:0xf bank_mask:0xf bound_ctrl:1
	v_add_f32_e32 v145, v75, v74
	v_mov_b32_e32 v74, v76
	s_or_b32 s14, s20, 8
	v_add_f32_dpp v77, v77, v77 row_mirror row_mask:0xf bank_mask:0xf bound_ctrl:1
	v_permlane16_swap_b32_e32 v76, v74
	s_lshl_b32 s15, s14, 10
	s_lshl_b32 s14, s14, 2
	v_add_f32_e32 v146, v76, v74
	v_mov_b32_e32 v74, v77
	s_add_i32 s16, s14, 0
	s_add_i32 s14, s21, 0x2400
	v_xor_b32_e32 v82, 0x90, v168
	v_permlane16_swap_b32_e32 v77, v74
	v_add_u32_e32 v141, s14, v82
	s_add_i32 s14, s21, 0x2800
	v_xor_b32_e32 v82, 0xa0, v168
	v_add_f32_e32 v147, v77, v74
	s_add_i32 s15, s15, 0
	v_xor_b32_e32 v74, 0x80, v168
	s_add_i32 s16, s16, 0x21400
	v_add_u32_e32 v142, s14, v82
	s_add_i32 s14, s21, 0x2c00
	v_xor_b32_e32 v82, 0xb0, v168
	v_add_u32_e32 v140, s15, v74
	v_mov_b32_e32 v78, s16
	v_add_u32_e32 v143, s14, v82
	ds_read_b128 v[74:77], v140
	ds_read_b128 v[78:81], v78
	ds_read_b128 v[86:89], v141
	ds_read_b128 v[90:93], v142
	ds_read_b128 v[82:85], v143
	v_mov_b32_e32 v170, v144
	v_mov_b32_e32 v171, v145
	v_mov_b32_e32 v172, v146
	v_mov_b32_e32 v173, v147
	v_permlane32_swap_b32_e32 v144, v170
	v_permlane32_swap_b32_e32 v145, v171
	v_permlane32_swap_b32_e32 v146, v172
	v_permlane32_swap_b32_e32 v147, v173
	v_lshlrev_b32_e32 v174, 16, v138
	v_and_b32_e32 v175, 0xffff0000, v138
	v_lshlrev_b32_e32 v138, 16, v139
	v_and_b32_e32 v139, 0xffff0000, v139
	s_waitcnt lgkmcnt(4)
	v_pk_mul_f32 v[76:77], v[72:73], v[76:77]
	v_pk_mul_f32 v[74:75], v[70:71], v[74:75]
	s_waitcnt lgkmcnt(3)
	v_pk_fma_f32 v[76:77], v[76:77], v[78:79], v[138:139] op_sel_hi:[1,0,1]
	v_pk_fma_f32 v[74:75], v[74:75], v[78:79], v[174:175] op_sel_hi:[1,0,1]
	s_and_b64 vcc, exec, s[42:43]
	v_add_u32_e32 v138, 0x4000, v157
	s_cbranch_vccnz .LBB0_445
	v_lshlrev_b32_e32 v139, 2, v138
	global_store_dwordx4 v139, v[74:77], s[8:9] sc1
	s_cbranch_execnz .LBB0_350
.LBB0_349:
	v_cvt_pk_bf16_f32 v174, v74, v75
	v_cvt_pk_bf16_f32 v175, v76, v77
	v_lshlrev_b32_e32 v138, 1, v138
	global_store_dwordx2 v138, v[174:175], s[4:5] sc1
.LBB0_350:
	v_lshlrev_b32_e32 v138, 16, v136
	v_and_b32_e32 v139, 0xffff0000, v136
	v_lshlrev_b32_e32 v136, 16, v137
	v_and_b32_e32 v137, 0xffff0000, v137
	s_waitcnt lgkmcnt(2)
	v_pk_mul_f32 v[88:89], v[72:73], v[88:89]
	v_pk_mul_f32 v[86:87], v[70:71], v[86:87]
	v_pk_fma_f32 v[88:89], v[88:89], v[78:79], v[136:137] op_sel:[0,1,0]
	v_pk_fma_f32 v[86:87], v[86:87], v[78:79], v[138:139] op_sel:[0,1,0]
	s_and_b64 vcc, exec, s[42:43]
	v_add_u32_e32 v78, 0x4800, v157
	s_cbranch_vccnz .LBB0_446
	v_lshlrev_b32_e32 v79, 2, v78
	global_store_dwordx4 v79, v[86:89], s[8:9] sc1
	s_cbranch_execnz .LBB0_353
.LBB0_352:
	v_cvt_pk_bf16_f32 v136, v86, v87
	v_cvt_pk_bf16_f32 v137, v88, v89
	v_lshlrev_b32_e32 v78, 1, v78
	global_store_dwordx2 v78, v[136:137], s[4:5] sc1
.LBB0_353:
	v_lshlrev_b32_e32 v78, 16, v134
	v_and_b32_e32 v79, 0xffff0000, v134
	v_lshlrev_b32_e32 v134, 16, v135
	v_and_b32_e32 v135, 0xffff0000, v135
	s_waitcnt lgkmcnt(1)
	v_pk_mul_f32 v[92:93], v[72:73], v[92:93]
	v_pk_mul_f32 v[90:91], v[70:71], v[90:91]
	v_pk_fma_f32 v[92:93], v[92:93], v[80:81], v[134:135] op_sel_hi:[1,0,1]
	v_pk_fma_f32 v[90:91], v[90:91], v[80:81], v[78:79] op_sel_hi:[1,0,1]
	s_and_b64 vcc, exec, s[42:43]
	v_add_u32_e32 v78, 0x5000, v157
	s_cbranch_vccnz .LBB0_447
	v_lshlrev_b32_e32 v79, 2, v78
	global_store_dwordx4 v79, v[90:93], s[8:9] sc1
	s_cbranch_execnz .LBB0_356
.LBB0_355:
	v_cvt_pk_bf16_f32 v134, v90, v91
	v_cvt_pk_bf16_f32 v135, v92, v93
	v_lshlrev_b32_e32 v78, 1, v78
	global_store_dwordx2 v78, v[134:135], s[4:5] sc1
.LBB0_356:
	v_lshlrev_b32_e32 v78, 16, v132
	v_and_b32_e32 v79, 0xffff0000, v132
	v_lshlrev_b32_e32 v132, 16, v133
	v_and_b32_e32 v133, 0xffff0000, v133
	s_waitcnt lgkmcnt(0)
	v_pk_mul_f32 v[84:85], v[72:73], v[84:85]
	v_pk_mul_f32 v[82:83], v[70:71], v[82:83]
	v_mov_b32_e32 v134, v81
	v_pk_fma_f32 v[80:81], v[84:85], v[134:135], v[132:133] op_sel_hi:[1,0,1]
	v_pk_fma_f32 v[78:79], v[82:83], v[134:135], v[78:79] op_sel_hi:[1,0,1]
	s_and_b64 vcc, exec, s[42:43]
	v_add_u32_e32 v82, 0x5800, v157
	s_cbranch_vccnz .LBB0_448
	v_lshlrev_b32_e32 v83, 2, v82
	global_store_dwordx4 v83, v[78:81], s[8:9] sc1
	s_cbranch_execnz .LBB0_359

;     __device__ __forceinline__ void fused(f32x4 (&acc)[2][2][4][2], const Unit& u, int wr, int wc, int fr, int fq, LAS unsigned char* lds, int wid, int lane) const {
;     ...
;             if (ai == 0) EN_ROWS(4); else EN_ROWS(8);
.LBB0_359:
	s_nop 0
	v_mul_f32_e32 v79, v79, v79
	v_fmac_f32_e32 v79, v78, v78
	v_mul_f32_e32 v78, v81, v81
	v_fmac_f32_e32 v78, v80, v80
	v_mul_f32_e32 v75, v75, v75
	v_add_f32_e32 v78, v79, v78
	v_mul_f32_e32 v79, v91, v91
	v_mul_f32_e32 v80, v93, v93
	v_fmac_f32_e32 v75, v74, v74
	v_mul_f32_e32 v74, v77, v77
	v_fmac_f32_e32 v79, v90, v90
	v_fmac_f32_e32 v80, v92, v92
	v_fmac_f32_e32 v74, v76, v76
	v_add_f32_e32 v79, v79, v80
	v_mul_f32_e32 v80, v87, v87
	v_mul_f32_e32 v81, v89, v89
	v_add_f32_e32 v74, v75, v74
	v_fmac_f32_e32 v80, v86, v86
	v_fmac_f32_e32 v81, v88, v88
	v_add_f32_dpp v74, v74, v74 quad_perm:[1,0,3,2] row_mask:0xf bank_mask:0xf bound_ctrl:1
	v_add_f32_e32 v80, v80, v81
	v_add_f32_dpp v76, v79, v79 quad_perm:[1,0,3,2] row_mask:0xf bank_mask:0xf bound_ctrl:1
	v_add_f32_dpp v74, v74, v74 quad_perm:[2,3,0,1] row_mask:0xf bank_mask:0xf bound_ctrl:1
	v_add_f32_dpp v75, v80, v80 quad_perm:[1,0,3,2] row_mask:0xf bank_mask:0xf bound_ctrl:1
	v_add_f32_dpp v77, v78, v78 quad_perm:[1,0,3,2] row_mask:0xf bank_mask:0xf bound_ctrl:1
	v_add_f32_dpp v74, v74, v74 row_half_mirror row_mask:0xf bank_mask:0xf bound_ctrl:1
	v_add_f32_dpp v75, v75, v75 quad_perm:[2,3,0,1] row_mask:0xf bank_mask:0xf bound_ctrl:1
	v_add_f32_dpp v76, v76, v76 quad_perm:[2,3,0,1] row_mask:0xf bank_mask:0xf bound_ctrl:1
	v_add_f32_dpp v74, v74, v74 row_mirror row_mask:0xf bank_mask:0xf bound_ctrl:1
	v_add_f32_dpp v75, v75, v75 row_half_mirror row_mask:0xf bank_mask:0xf bound_ctrl:1
	v_mov_b32_e32 v78, v74
	s_nop 1
	v_permlane16_swap_b32_e32 v74, v78
	v_add_f32_dpp v75, v75, v75 row_mirror row_mask:0xf bank_mask:0xf bound_ctrl:1
	v_add_f32_dpp v76, v76, v76 row_half_mirror row_mask:0xf bank_mask:0xf bound_ctrl:1
	v_add_f32_e32 v136, v74, v78
	v_mov_b32_e32 v74, v75
	v_add_f32_dpp v77, v77, v77 quad_perm:[2,3,0,1] row_mask:0xf bank_mask:0xf bound_ctrl:1
	v_add_f32_dpp v76, v76, v76 row_mirror row_mask:0xf bank_mask:0xf bound_ctrl:1
	v_permlane16_swap_b32_e32 v75, v74
	v_add_f32_dpp v77, v77, v77 row_half_mirror row_mask:0xf bank_mask:0xf bound_ctrl:1
	v_add_f32_e32 v137, v75, v74
	v_mov_b32_e32 v74, v76
	s_or_b32 s14, s20, 12
	v_add_f32_dpp v77, v77, v77 row_mirror row_mask:0xf bank_mask:0xf bound_ctrl:1
	v_permlane16_swap_b32_e32 v76, v74
	s_lshl_b32 s15, s14, 10
	s_lshl_b32 s14, s14, 2
	v_add_f32_e32 v138, v76, v74
	v_mov_b32_e32 v74, v77
	s_add_i32 s19, s14, 0
	s_add_i32 s14, s21, 0x3400
	v_xor_b32_e32 v82, 0xd0, v168
	v_permlane16_swap_b32_e32 v77, v74
	v_add_u32_e32 v133, s14, v82
	s_add_i32 s14, s21, 0x3800
	v_xor_b32_e32 v82, 0xe0, v168
	v_add_f32_e32 v139, v77, v74
	s_add_i32 s15, s15, 0
	v_xor_b32_e32 v74, 0xc0, v168
	s_add_i32 s19, s19, 0x21400
	v_add_u32_e32 v134, s14, v82
	s_addk_i32 s21, 0x3c00
	v_xor_b32_e32 v82, 0xf0, v168
	v_add_u32_e32 v132, s15, v74
	v_mov_b32_e32 v78, s19
	v_add_u32_e32 v135, s21, v82
	ds_read_b128 v[74:77], v132
	ds_read_b128 v[78:81], v78
	ds_read_b128 v[86:89], v133
	ds_read_b128 v[90:93], v134
	ds_read_b128 v[82:85], v135
	v_mov_b32_e32 v174, v136
	v_mov_b32_e32 v175, v137
	v_mov_b32_e32 v176, v138
	v_mov_b32_e32 v168, v139
	v_permlane32_swap_b32_e32 v136, v174
	v_permlane32_swap_b32_e32 v137, v175
	v_permlane32_swap_b32_e32 v138, v176
	v_permlane32_swap_b32_e32 v139, v168
	v_lshlrev_b32_e32 v178, 16, v130
	v_and_b32_e32 v179, 0xffff0000, v130
	v_lshlrev_b32_e32 v130, 16, v131
	v_and_b32_e32 v131, 0xffff0000, v131
	s_waitcnt lgkmcnt(4)
	v_pk_mul_f32 v[76:77], v[72:73], v[76:77]
	v_pk_mul_f32 v[74:75], v[70:71], v[74:75]
	s_waitcnt lgkmcnt(3)
	v_pk_fma_f32 v[76:77], v[76:77], v[78:79], v[130:131] op_sel_hi:[1,0,1]
	v_pk_fma_f32 v[74:75], v[74:75], v[78:79], v[178:179] op_sel_hi:[1,0,1]
	s_and_b64 vcc, exec, s[42:43]
	v_add_u32_e32 v130, 0x6000, v157
	s_cbranch_vccnz .LBB0_449
	v_lshlrev_b32_e32 v131, 2, v130
	global_store_dwordx4 v131, v[74:77], s[8:9] sc1
	s_cbranch_execnz .LBB0_362
.LBB0_361:
	v_cvt_pk_bf16_f32 v178, v74, v75
	v_cvt_pk_bf16_f32 v179, v76, v77
	v_lshlrev_b32_e32 v130, 1, v130
	global_store_dwordx2 v130, v[178:179], s[4:5] sc1
.LBB0_362:
	v_lshlrev_b32_e32 v130, 16, v128
	v_and_b32_e32 v131, 0xffff0000, v128
	v_lshlrev_b32_e32 v128, 16, v129
	v_and_b32_e32 v129, 0xffff0000, v129
	s_waitcnt lgkmcnt(2)
	v_pk_mul_f32 v[88:89], v[72:73], v[88:89]
	v_pk_mul_f32 v[86:87], v[70:71], v[86:87]
	v_pk_fma_f32 v[88:89], v[88:89], v[78:79], v[128:129] op_sel:[0,1,0]
	v_pk_fma_f32 v[86:87], v[86:87], v[78:79], v[130:131] op_sel:[0,1,0]
	s_and_b64 vcc, exec, s[42:43]
	v_add_u32_e32 v78, 0x6800, v157
	s_cbranch_vccnz .LBB0_450
	v_lshlrev_b32_e32 v79, 2, v78
	global_store_dwordx4 v79, v[86:89], s[8:9] sc1
	s_cbranch_execnz .LBB0_365
.LBB0_364:
	v_cvt_pk_bf16_f32 v128, v86, v87
	v_cvt_pk_bf16_f32 v129, v88, v89
	v_lshlrev_b32_e32 v78, 1, v78
	global_store_dwordx2 v78, v[128:129], s[4:5] sc1
.LBB0_365:
	v_lshlrev_b32_e32 v78, 16, v126
	v_and_b32_e32 v79, 0xffff0000, v126
	v_lshlrev_b32_e32 v126, 16, v127
	v_and_b32_e32 v127, 0xffff0000, v127
	s_waitcnt lgkmcnt(1)
	v_pk_mul_f32 v[92:93], v[72:73], v[92:93]
	v_pk_mul_f32 v[90:91], v[70:71], v[90:91]
	v_pk_fma_f32 v[92:93], v[92:93], v[80:81], v[126:127] op_sel_hi:[1,0,1]
	v_pk_fma_f32 v[90:91], v[90:91], v[80:81], v[78:79] op_sel_hi:[1,0,1]
	s_and_b64 vcc, exec, s[42:43]
	v_add_u32_e32 v78, 0x7000, v157
	s_cbranch_vccnz .LBB0_451
	v_lshlrev_b32_e32 v79, 2, v78
	global_store_dwordx4 v79, v[90:93], s[8:9] sc1
	s_cbranch_execnz .LBB0_368
.LBB0_367:
	v_cvt_pk_bf16_f32 v126, v90, v91
	v_cvt_pk_bf16_f32 v127, v92, v93
	v_lshlrev_b32_e32 v78, 1, v78
	global_store_dwordx2 v78, v[126:127], s[4:5] sc1
.LBB0_368:
	v_lshlrev_b32_e32 v78, 16, v124
	v_and_b32_e32 v79, 0xffff0000, v124
	v_lshlrev_b32_e32 v124, 16, v125
	v_and_b32_e32 v125, 0xffff0000, v125
	s_waitcnt lgkmcnt(0)
	v_pk_mul_f32 v[84:85], v[72:73], v[84:85]
	v_pk_mul_f32 v[82:83], v[70:71], v[82:83]
	v_mov_b32_e32 v126, v81
	v_pk_fma_f32 v[80:81], v[84:85], v[126:127], v[124:125] op_sel_hi:[1,0,1]
	v_pk_fma_f32 v[78:79], v[82:83], v[126:127], v[78:79] op_sel_hi:[1,0,1]
	s_and_b64 vcc, exec, s[42:43]
	v_add_u32_e32 v82, 0x7800, v157
	s_cbranch_vccnz .LBB0_452
	v_lshlrev_b32_e32 v83, 2, v82
	global_store_dwordx4 v83, v[78:81], s[8:9] sc1
	s_cbranch_execnz .LBB0_371

; #define LAS __attribute__((address_space(3)))
;     __device__ __forceinline__ HT hload(unsigned eoff) const { const u32x2 a = *(const u32x2*)((const char*)hi + eoff * 2u); const u32x2 b = *(const u32x2*)((const char*)lo + eoff * 2u); return (u32x4){a.x, a.y, b.x, b.y}; }
;     __device__ __forceinline__ void fused(f32x4 (&acc)[2][2][4][2], const Unit& u, int wr, int wc, int fr, int fq, LAS unsigned char* lds, int wid, int lane) const {
;     ...
;             if (ai == 1) {
; #pragma unroll
;             for (int m = 0; m < 4; ++m)
; #pragma unroll
;                 for (int bj = 0; bj < 2; ++bj)
; #pragma unroll
;                     for (int n = 0; n < 2; ++n) { const int r = wr * 64 + m * 16 + fr, c16 = 32 * bj + 8 * wc + 4 * n + fq;
;                         *(LAS f32x4*)(lds + r * 1024 + ((c16 ^ (r & 15)) << 4)) = acc[1][bj][m][n]; }
;             }
;             asm volatile("s_waitcnt lgkmcnt(0)" ::: "memory"); __builtin_amdgcn_s_barrier(); asm volatile("" ::: "memory");
;             if (ai == 0) {
;                 asm volatile("" :: "v"(H[0]), "v"(H[1]), "v"(H[2]), "v"(H[3]), "v"(H[4]), "v"(H[5]), "v"(H[6]), "v"(H[7]), "v"(H[8]), "v"(H[9]), "v"(H[10]), "v"(H[11]), "v"(H[12]), "v"(H[13]), "v"(H[14]), "v"(H[15]));
; #pragma unroll
;                 for (int j = 0; j < 16; ++j) H2[j] = hload(rbase + (unsigned)((HALF + j) * D));
;             }
;             float sqt = 0.f;
;     ...
;             if (ai == 0) EN_ROWS(4); else EN_ROWS(8);
.LBB0_373:
	s_or_b64 exec, exec, s[14:15]
	s_waitcnt lgkmcnt(0)
	s_barrier
	ds_write_b128 v158, v[66:69]
	ds_write_b128 v159, v[62:65]
	ds_write_b128 v160, v[46:49]
	ds_write_b128 v161, v[38:41]
	ds_write_b128 v158, v[58:61] offset:16384
	ds_write_b128 v159, v[54:57] offset:16384
	ds_write_b128 v160, v[30:33] offset:16384
	ds_write_b128 v161, v[22:25] offset:16384
	ds_write_b128 v158, v[50:53] offset:32768
	ds_write_b128 v159, v[42:45] offset:32768
	ds_write_b128 v160, v[18:21] offset:32768
	ds_write_b128 v161, v[14:17] offset:32768
	ds_write_b128 v158, v[34:37] offset:49152
	ds_write_b128 v159, v[26:29] offset:49152
	ds_write_b128 v160, v[10:13] offset:49152
	ds_write_b128 v161, v[6:9] offset:49152
	s_waitcnt lgkmcnt(0)
	s_barrier
	v_mov_b32_e32 v14, s18
	ds_read_b128 v[6:9], v4
	ds_read_b128 v[10:13], v162
	ds_read_b128 v[22:25], v163
	ds_read_b128 v[42:45], v164
	v_mov_b32_e32 v4, s17
	ds_read_b128 v[30:33], v14 offset:512
	ds_read_b128 v[14:17], v4 offset:512
	ds_read_b128 v[38:41], v148
	ds_read_b128 v[34:37], v149
	ds_read_b128 v[26:29], v150
	ds_read_b128 v[18:21], v151
	v_add_u32_e32 v4, 0x40000, v157
	s_waitcnt vmcnt(15)
	v_lshlrev_b32_e32 v46, 16, v122
	v_and_b32_e32 v47, 0xffff0000, v122
	v_lshlrev_b32_e32 v48, 16, v123
	v_and_b32_e32 v49, 0xffff0000, v123
	s_waitcnt lgkmcnt(9)
	v_pk_mul_f32 v[8:9], v[72:73], v[8:9]
	v_pk_mul_f32 v[6:7], v[70:71], v[6:7]
	s_waitcnt lgkmcnt(5)
	v_pk_fma_f32 v[8:9], v[8:9], v[30:31], v[48:49] op_sel_hi:[1,0,1]
	s_and_b64 vcc, exec, s[42:43]
	v_pk_fma_f32 v[6:7], v[6:7], v[30:31], v[46:47] op_sel_hi:[1,0,1]
	s_cbranch_vccnz .LBB0_453
	v_lshlrev_b32_e32 v46, 2, v4
	global_store_dwordx4 v46, v[6:9], s[8:9] sc1
	s_cbranch_execnz .LBB0_376
.LBB0_375:
	v_cvt_pk_bf16_f32 v46, v6, v7
	v_cvt_pk_bf16_f32 v47, v8, v9
	v_lshlrev_b32_e32 v4, 1, v4
	global_store_dwordx2 v4, v[46:47], s[4:5] sc1
.LBB0_376:
	s_waitcnt vmcnt(14)
	v_lshlrev_b32_e32 v46, 16, v120
	v_and_b32_e32 v47, 0xffff0000, v120
	v_lshlrev_b32_e32 v48, 16, v121
	v_and_b32_e32 v49, 0xffff0000, v121
	v_pk_mul_f32 v[12:13], v[72:73], v[12:13]
	v_pk_mul_f32 v[10:11], v[70:71], v[10:11]
	v_pk_fma_f32 v[12:13], v[12:13], v[30:31], v[48:49] op_sel:[0,1,0]
	v_pk_fma_f32 v[10:11], v[10:11], v[30:31], v[46:47] op_sel:[0,1,0]
	s_and_b64 vcc, exec, s[42:43]
	v_add_u32_e32 v4, 0x40800, v157
	s_cbranch_vccnz .LBB0_454
	v_lshlrev_b32_e32 v30, 2, v4
	global_store_dwordx4 v30, v[10:13], s[8:9] sc1
	s_cbranch_execnz .LBB0_379
.LBB0_378:
	v_cvt_pk_bf16_f32 v30, v10, v11
	v_cvt_pk_bf16_f32 v31, v12, v13
	v_lshlrev_b32_e32 v4, 1, v4
	global_store_dwordx2 v4, v[30:31], s[4:5] sc1
.LBB0_379:
	s_waitcnt vmcnt(13)
	v_lshlrev_b32_e32 v30, 16, v118
	v_and_b32_e32 v31, 0xffff0000, v118
	v_lshlrev_b32_e32 v46, 16, v119
	v_and_b32_e32 v47, 0xffff0000, v119
	v_pk_mul_f32 v[24:25], v[72:73], v[24:25]
	v_pk_mul_f32 v[22:23], v[70:71], v[22:23]
	v_pk_fma_f32 v[24:25], v[24:25], v[32:33], v[46:47] op_sel_hi:[1,0,1]
	v_pk_fma_f32 v[22:23], v[22:23], v[32:33], v[30:31] op_sel_hi:[1,0,1]
	s_and_b64 vcc, exec, s[42:43]
	v_add_u32_e32 v4, 0x41000, v157
	s_cbranch_vccnz .LBB0_455
	v_lshlrev_b32_e32 v30, 2, v4
	global_store_dwordx4 v30, v[22:25], s[8:9] sc1
	s_cbranch_execnz .LBB0_382
.LBB0_381:
	v_cvt_pk_bf16_f32 v30, v22, v23
	v_cvt_pk_bf16_f32 v31, v24, v25
	v_lshlrev_b32_e32 v4, 1, v4
	global_store_dwordx2 v4, v[30:31], s[4:5] sc1
.LBB0_382:
	s_waitcnt vmcnt(12)
	v_lshlrev_b32_e32 v30, 16, v116
	v_and_b32_e32 v31, 0xffff0000, v116
	v_lshlrev_b32_e32 v46, 16, v117
	v_and_b32_e32 v47, 0xffff0000, v117
	v_pk_mul_f32 v[44:45], v[72:73], v[44:45]
	v_pk_mul_f32 v[42:43], v[70:71], v[42:43]
	v_mov_b32_e32 v4, v33
	v_pk_fma_f32 v[32:33], v[44:45], v[4:5], v[46:47] op_sel_hi:[1,0,1]
	v_pk_fma_f32 v[30:31], v[42:43], v[4:5], v[30:31] op_sel_hi:[1,0,1]
	s_and_b64 vcc, exec, s[42:43]
	v_add_u32_e32 v4, 0x41800, v157
	s_cbranch_vccnz .LBB0_456
	v_lshlrev_b32_e32 v42, 2, v4
	global_store_dwordx4 v42, v[30:33], s[8:9] sc1
	s_cbranch_execnz .LBB0_385
.LBB0_384:
	v_cvt_pk_bf16_f32 v42, v30, v31
	v_cvt_pk_bf16_f32 v43, v32, v33
	v_lshlrev_b32_e32 v4, 1, v4
	global_store_dwordx2 v4, v[42:43], s[4:5] sc1
.LBB0_385:
	s_waitcnt vmcnt(11)
	v_lshlrev_b32_e32 v42, 16, v114
	v_and_b32_e32 v43, 0xffff0000, v114
	v_lshlrev_b32_e32 v44, 16, v115
	v_and_b32_e32 v45, 0xffff0000, v115
	s_waitcnt lgkmcnt(3)
	v_pk_mul_f32 v[40:41], v[72:73], v[40:41]
	v_pk_mul_f32 v[38:39], v[70:71], v[38:39]
	v_pk_fma_f32 v[40:41], v[40:41], v[14:15], v[44:45] op_sel_hi:[1,0,1]
	v_pk_fma_f32 v[38:39], v[38:39], v[14:15], v[42:43] op_sel_hi:[1,0,1]
	s_and_b64 vcc, exec, s[42:43]
	v_add_u32_e32 v4, 0x42000, v157
	s_cbranch_vccnz .LBB0_457
	v_lshlrev_b32_e32 v42, 2, v4
	global_store_dwordx4 v42, v[38:41], s[8:9] sc1
	s_cbranch_execnz .LBB0_388
.LBB0_387:
	v_cvt_pk_bf16_f32 v42, v38, v39
	v_cvt_pk_bf16_f32 v43, v40, v41
	v_lshlrev_b32_e32 v4, 1, v4
	global_store_dwordx2 v4, v[42:43], s[4:5] sc1
.LBB0_388:
	s_waitcnt vmcnt(10)
	v_lshlrev_b32_e32 v42, 16, v112
	v_and_b32_e32 v43, 0xffff0000, v112
	v_lshlrev_b32_e32 v44, 16, v113
	v_and_b32_e32 v45, 0xffff0000, v113
	s_waitcnt lgkmcnt(2)
	v_pk_mul_f32 v[36:37], v[72:73], v[36:37]
	v_pk_mul_f32 v[34:35], v[70:71], v[34:35]
	v_pk_fma_f32 v[36:37], v[36:37], v[14:15], v[44:45] op_sel:[0,1,0]
	v_pk_fma_f32 v[34:35], v[34:35], v[14:15], v[42:43] op_sel:[0,1,0]
	s_and_b64 vcc, exec, s[42:43]
	v_add_u32_e32 v4, 0x42800, v157
	s_cbranch_vccnz .LBB0_458
	v_lshlrev_b32_e32 v14, 2, v4
	global_store_dwordx4 v14, v[34:37], s[8:9] sc1
	s_cbranch_execnz .LBB0_391
.LBB0_390:
	v_cvt_pk_bf16_f32 v14, v34, v35
	v_cvt_pk_bf16_f32 v15, v36, v37
	v_lshlrev_b32_e32 v4, 1, v4
	global_store_dwordx2 v4, v[14:15], s[4:5] sc1
;     __device__ __forceinline__ void fused(f32x4 (&acc)[2][2][4][2], const Unit& u, int wr, int wc, int fr, int fq, LAS unsigned char* lds, int wid, int lane) const {
;     ...
;             if (ai == 0) EN_ROWS(4); else EN_ROWS(8);
.LBB0_391:
	s_waitcnt vmcnt(9)
	v_lshlrev_b32_e32 v14, 16, v110
	v_and_b32_e32 v15, 0xffff0000, v110
	v_lshlrev_b32_e32 v42, 16, v111
	v_and_b32_e32 v43, 0xffff0000, v111
	s_waitcnt lgkmcnt(1)
	v_pk_mul_f32 v[28:29], v[72:73], v[28:29]
	v_pk_mul_f32 v[26:27], v[70:71], v[26:27]
	v_pk_fma_f32 v[28:29], v[28:29], v[16:17], v[42:43] op_sel_hi:[1,0,1]
	v_pk_fma_f32 v[26:27], v[26:27], v[16:17], v[14:15] op_sel_hi:[1,0,1]
	s_and_b64 vcc, exec, s[42:43]
	v_add_u32_e32 v4, 0x43000, v157
	s_cbranch_vccnz .LBB0_459
	v_lshlrev_b32_e32 v14, 2, v4
	global_store_dwordx4 v14, v[26:29], s[8:9] sc1
	s_cbranch_execnz .LBB0_394
.LBB0_393:
	v_cvt_pk_bf16_f32 v14, v26, v27
	v_cvt_pk_bf16_f32 v15, v28, v29
	v_lshlrev_b32_e32 v4, 1, v4
	global_store_dwordx2 v4, v[14:15], s[4:5] sc1
.LBB0_394:
	s_waitcnt vmcnt(8)
	v_lshlrev_b32_e32 v14, 16, v108
	v_and_b32_e32 v15, 0xffff0000, v108
	v_lshlrev_b32_e32 v42, 16, v109
	v_and_b32_e32 v43, 0xffff0000, v109
	s_waitcnt lgkmcnt(0)
	v_pk_mul_f32 v[20:21], v[72:73], v[20:21]
	v_pk_mul_f32 v[18:19], v[70:71], v[18:19]
	v_mov_b32_e32 v4, v17
	v_pk_fma_f32 v[16:17], v[20:21], v[4:5], v[42:43] op_sel_hi:[1,0,1]
	v_pk_fma_f32 v[14:15], v[18:19], v[4:5], v[14:15] op_sel_hi:[1,0,1]
	s_and_b64 vcc, exec, s[42:43]
	v_add_u32_e32 v4, 0x43800, v157
	s_cbranch_vccnz .LBB0_460
	v_lshlrev_b32_e32 v18, 2, v4
	global_store_dwordx4 v18, v[14:17], s[8:9] sc1
	s_cbranch_execnz .LBB0_397
.LBB0_396:
	v_cvt_pk_bf16_f32 v18, v14, v15
	v_cvt_pk_bf16_f32 v19, v16, v17
	v_lshlrev_b32_e32 v4, 1, v4
	global_store_dwordx2 v4, v[18:19], s[4:5] sc1
.LBB0_397:
	v_mul_f32_e32 v4, v15, v15
	v_fmac_f32_e32 v4, v14, v14
	v_mul_f32_e32 v14, v17, v17
	v_fmac_f32_e32 v14, v16, v16
	v_add_f32_e32 v4, v4, v14
	v_mul_f32_e32 v14, v27, v27
	v_mul_f32_e32 v15, v29, v29
	v_fmac_f32_e32 v14, v26, v26
	v_fmac_f32_e32 v15, v28, v28
	v_add_f32_e32 v14, v14, v15
	v_mul_f32_e32 v15, v35, v35
	v_mul_f32_e32 v16, v37, v37
	v_fmac_f32_e32 v15, v34, v34
	v_fmac_f32_e32 v16, v36, v36
	v_mul_f32_e32 v7, v7, v7
	v_add_f32_e32 v15, v15, v16
	v_mul_f32_e32 v16, v39, v39
	v_mul_f32_e32 v17, v41, v41
	v_fmac_f32_e32 v7, v6, v6
	v_mul_f32_e32 v6, v9, v9
	v_fmac_f32_e32 v16, v38, v38
	v_fmac_f32_e32 v17, v40, v40
	v_mul_f32_e32 v11, v11, v11
	v_fmac_f32_e32 v6, v8, v8
	v_add_f32_e32 v16, v16, v17
	v_mul_f32_e32 v17, v31, v31
	v_mul_f32_e32 v18, v33, v33
	v_fmac_f32_e32 v11, v10, v10
	v_mul_f32_e32 v10, v13, v13
	v_add_f32_e32 v6, v7, v6
	v_fmac_f32_e32 v17, v30, v30
	v_fmac_f32_e32 v18, v32, v32
	v_fmac_f32_e32 v10, v12, v12
	v_add_f32_dpp v6, v6, v6 quad_perm:[1,0,3,2] row_mask:0xf bank_mask:0xf bound_ctrl:1
	v_add_f32_e32 v17, v17, v18
	v_mul_f32_e32 v18, v23, v23
	v_mul_f32_e32 v19, v25, v25
	v_add_f32_e32 v10, v11, v10
	v_add_f32_dpp v4, v4, v4 quad_perm:[1,0,3,2] row_mask:0xf bank_mask:0xf bound_ctrl:1
	v_add_f32_dpp v6, v6, v6 quad_perm:[2,3,0,1] row_mask:0xf bank_mask:0xf bound_ctrl:1
	v_fmac_f32_e32 v18, v22, v22
	v_fmac_f32_e32 v19, v24, v24
	v_add_f32_dpp v7, v10, v10 quad_perm:[1,0,3,2] row_mask:0xf bank_mask:0xf bound_ctrl:1
	v_add_f32_dpp v4, v4, v4 quad_perm:[2,3,0,1] row_mask:0xf bank_mask:0xf bound_ctrl:1
	v_add_f32_dpp v6, v6, v6 row_half_mirror row_mask:0xf bank_mask:0xf bound_ctrl:1
	v_add_f32_e32 v18, v18, v19
	v_add_f32_dpp v7, v7, v7 quad_perm:[2,3,0,1] row_mask:0xf bank_mask:0xf bound_ctrl:1
	v_add_f32_dpp v4, v4, v4 row_half_mirror row_mask:0xf bank_mask:0xf bound_ctrl:1
	v_add_f32_dpp v6, v6, v6 row_mirror row_mask:0xf bank_mask:0xf bound_ctrl:1
	v_add_f32_dpp v8, v18, v18 quad_perm:[1,0,3,2] row_mask:0xf bank_mask:0xf bound_ctrl:1
	v_add_f32_dpp v7, v7, v7 row_half_mirror row_mask:0xf bank_mask:0xf bound_ctrl:1
	v_add_f32_dpp v13, v4, v4 row_mirror row_mask:0xf bank_mask:0xf bound_ctrl:1
	v_mov_b32_e32 v4, v6
	v_add_f32_dpp v8, v8, v8 quad_perm:[2,3,0,1] row_mask:0xf bank_mask:0xf bound_ctrl:1
	v_add_f32_dpp v7, v7, v7 row_mirror row_mask:0xf bank_mask:0xf bound_ctrl:1
	v_permlane16_swap_b32_e32 v6, v4
	v_add_f32_dpp v9, v17, v17 quad_perm:[1,0,3,2] row_mask:0xf bank_mask:0xf bound_ctrl:1
	v_add_f32_dpp v8, v8, v8 row_half_mirror row_mask:0xf bank_mask:0xf bound_ctrl:1
	v_add_f32_e32 v4, v6, v4
	v_mov_b32_e32 v6, v7
	v_add_f32_dpp v9, v9, v9 quad_perm:[2,3,0,1] row_mask:0xf bank_mask:0xf bound_ctrl:1
	v_add_f32_dpp v8, v8, v8 row_mirror row_mask:0xf bank_mask:0xf bound_ctrl:1
	v_permlane16_swap_b32_e32 v7, v6
	v_add_f32_dpp v10, v16, v16 quad_perm:[1,0,3,2] row_mask:0xf bank_mask:0xf bound_ctrl:1
	v_add_f32_dpp v9, v9, v9 row_half_mirror row_mask:0xf bank_mask:0xf bound_ctrl:1
	v_add_f32_e32 v46, v7, v6
	v_mov_b32_e32 v6, v8
	v_add_f32_dpp v10, v10, v10 quad_perm:[2,3,0,1] row_mask:0xf bank_mask:0xf bound_ctrl:1
	v_add_f32_dpp v9, v9, v9 row_mirror row_mask:0xf bank_mask:0xf bound_ctrl:1
	v_permlane16_swap_b32_e32 v8, v6
	v_add_f32_dpp v11, v15, v15 quad_perm:[1,0,3,2] row_mask:0xf bank_mask:0xf bound_ctrl:1
	v_add_f32_dpp v10, v10, v10 row_half_mirror row_mask:0xf bank_mask:0xf bound_ctrl:1
	v_add_f32_e32 v47, v8, v6
	v_mov_b32_e32 v6, v9
	v_add_f32_dpp v11, v11, v11 quad_perm:[2,3,0,1] row_mask:0xf bank_mask:0xf bound_ctrl:1
	v_add_f32_dpp v10, v10, v10 row_mirror row_mask:0xf bank_mask:0xf bound_ctrl:1
	v_permlane16_swap_b32_e32 v9, v6
	v_add_f32_dpp v12, v14, v14 quad_perm:[1,0,3,2] row_mask:0xf bank_mask:0xf bound_ctrl:1
	v_add_f32_dpp v11, v11, v11 row_half_mirror row_mask:0xf bank_mask:0xf bound_ctrl:1
	v_add_f32_e32 v48, v9, v6
	v_mov_b32_e32 v6, v10
	v_add_f32_dpp v12, v12, v12 quad_perm:[2,3,0,1] row_mask:0xf bank_mask:0xf bound_ctrl:1
	v_add_f32_dpp v11, v11, v11 row_mirror row_mask:0xf bank_mask:0xf bound_ctrl:1
	v_permlane16_swap_b32_e32 v10, v6
	v_add_f32_dpp v12, v12, v12 row_half_mirror row_mask:0xf bank_mask:0xf bound_ctrl:1
	v_add_f32_e32 v49, v10, v6
	v_mov_b32_e32 v6, v11
	v_add_f32_dpp v12, v12, v12 row_mirror row_mask:0xf bank_mask:0xf bound_ctrl:1
	s_nop 0
	v_permlane16_swap_b32_e32 v11, v6
	v_add_f32_e32 v50, v11, v6
	v_mov_b32_e32 v6, v12
	s_nop 1
	v_permlane16_swap_b32_e32 v12, v6
	v_add_f32_e32 v51, v12, v6
	v_mov_b32_e32 v6, v13
	s_nop 1
	v_permlane16_swap_b32_e32 v13, v6
	v_mov_b32_e32 v14, s16
	v_mov_b32_e32 v15, s19
	v_add_f32_e32 v52, v13, v6
	ds_read_b128 v[6:9], v140
	ds_read_b128 v[10:13], v141
	ds_read_b128 v[22:25], v142
	ds_read_b128 v[42:45], v143
	ds_read_b128 v[30:33], v14 offset:512
	ds_read_b128 v[14:17], v15 offset:512
	ds_read_b128 v[38:41], v132
	ds_read_b128 v[34:37], v133
	ds_read_b128 v[26:29], v134
	ds_read_b128 v[18:21], v135
	v_mov_b32_e32 v53, v4
	v_mov_b32_e32 v54, v46
	v_mov_b32_e32 v55, v47
	v_mov_b32_e32 v56, v48
	v_mov_b32_e32 v57, v49
	v_mov_b32_e32 v58, v50
	v_mov_b32_e32 v59, v51
	v_mov_b32_e32 v60, v52
	v_permlane32_swap_b32_e32 v4, v53
	v_permlane32_swap_b32_e32 v46, v54
	v_permlane32_swap_b32_e32 v47, v55
	v_permlane32_swap_b32_e32 v48, v56
	v_permlane32_swap_b32_e32 v49, v57
	v_permlane32_swap_b32_e32 v50, v58
	v_permlane32_swap_b32_e32 v51, v59
	v_permlane32_swap_b32_e32 v52, v60
	s_waitcnt vmcnt(7)
;     __device__ __forceinline__ void fused(f32x4 (&acc)[2][2][4][2], const Unit& u, int wr, int wc, int fr, int fq, LAS unsigned char* lds, int wid, int lane) const {
;     ...
;             if (ai == 0) EN_ROWS(4); else EN_ROWS(8);
	v_lshlrev_b32_e32 v62, 16, v106
	v_and_b32_e32 v63, 0xffff0000, v106
	v_lshlrev_b32_e32 v64, 16, v107
	v_and_b32_e32 v65, 0xffff0000, v107
	s_waitcnt lgkmcnt(9)
	v_pk_mul_f32 v[8:9], v[72:73], v[8:9]
	v_pk_mul_f32 v[6:7], v[70:71], v[6:7]
	s_waitcnt lgkmcnt(5)
	v_pk_fma_f32 v[8:9], v[8:9], v[30:31], v[64:65] op_sel_hi:[1,0,1]
	v_pk_fma_f32 v[6:7], v[6:7], v[30:31], v[62:63] op_sel_hi:[1,0,1]
	s_and_b64 vcc, exec, s[42:43]
	v_add_u32_e32 v61, 0x44000, v157
	s_cbranch_vccnz .LBB0_461
	v_lshlrev_b32_e32 v62, 2, v61
	global_store_dwordx4 v62, v[6:9], s[8:9] sc1
	s_cbranch_execnz .LBB0_400
.LBB0_399:
	v_cvt_pk_bf16_f32 v62, v6, v7
	v_cvt_pk_bf16_f32 v63, v8, v9
	v_lshlrev_b32_e32 v61, 1, v61
	global_store_dwordx2 v61, v[62:63], s[4:5] sc1
.LBB0_400:
	s_waitcnt vmcnt(6)
	v_lshlrev_b32_e32 v62, 16, v104
	v_and_b32_e32 v63, 0xffff0000, v104
	v_lshlrev_b32_e32 v64, 16, v105
	v_and_b32_e32 v65, 0xffff0000, v105
	v_pk_mul_f32 v[12:13], v[72:73], v[12:13]
	v_pk_mul_f32 v[10:11], v[70:71], v[10:11]
	v_pk_fma_f32 v[12:13], v[12:13], v[30:31], v[64:65] op_sel:[0,1,0]
	v_pk_fma_f32 v[10:11], v[10:11], v[30:31], v[62:63] op_sel:[0,1,0]
	s_and_b64 vcc, exec, s[42:43]
	v_add_u32_e32 v30, 0x44800, v157
	s_cbranch_vccnz .LBB0_462
	v_lshlrev_b32_e32 v31, 2, v30
	global_store_dwordx4 v31, v[10:13], s[8:9] sc1
	s_cbranch_execnz .LBB0_403
.LBB0_402:
	v_cvt_pk_bf16_f32 v62, v10, v11
	v_cvt_pk_bf16_f32 v63, v12, v13
	v_lshlrev_b32_e32 v30, 1, v30
	global_store_dwordx2 v30, v[62:63], s[4:5] sc1
.LBB0_403:
	s_waitcnt vmcnt(5)
	v_lshlrev_b32_e32 v30, 16, v102
	v_and_b32_e32 v31, 0xffff0000, v102
	v_lshlrev_b32_e32 v62, 16, v103
	v_and_b32_e32 v63, 0xffff0000, v103
	v_pk_mul_f32 v[24:25], v[72:73], v[24:25]
	v_pk_mul_f32 v[22:23], v[70:71], v[22:23]
	v_pk_fma_f32 v[24:25], v[24:25], v[32:33], v[62:63] op_sel_hi:[1,0,1]
	v_pk_fma_f32 v[22:23], v[22:23], v[32:33], v[30:31] op_sel_hi:[1,0,1]
	s_and_b64 vcc, exec, s[42:43]
	v_add_u32_e32 v30, 0x45000, v157
	s_cbranch_vccnz .LBB0_463
	v_lshlrev_b32_e32 v31, 2, v30
	global_store_dwordx4 v31, v[22:25], s[8:9] sc1
	s_cbranch_execnz .LBB0_406
.LBB0_405:
	v_cvt_pk_bf16_f32 v62, v22, v23
	v_cvt_pk_bf16_f32 v63, v24, v25
	v_lshlrev_b32_e32 v30, 1, v30
	global_store_dwordx2 v30, v[62:63], s[4:5] sc1
.LBB0_406:
	s_waitcnt vmcnt(4)
	v_lshlrev_b32_e32 v30, 16, v100
	v_and_b32_e32 v31, 0xffff0000, v100
	v_lshlrev_b32_e32 v62, 16, v101
	v_and_b32_e32 v63, 0xffff0000, v101
	v_pk_mul_f32 v[44:45], v[72:73], v[44:45]
	v_pk_mul_f32 v[42:43], v[70:71], v[42:43]
	v_mov_b32_e32 v64, v33
	v_pk_fma_f32 v[32:33], v[44:45], v[64:65], v[62:63] op_sel_hi:[1,0,1]
	v_pk_fma_f32 v[30:31], v[42:43], v[64:65], v[30:31] op_sel_hi:[1,0,1]
	s_and_b64 vcc, exec, s[42:43]
	v_add_u32_e32 v42, 0x45800, v157
	s_cbranch_vccnz .LBB0_464
	v_lshlrev_b32_e32 v43, 2, v42
	global_store_dwordx4 v43, v[30:33], s[8:9] sc1
	s_cbranch_execnz .LBB0_409
.LBB0_408:
	v_cvt_pk_bf16_f32 v44, v30, v31
	v_cvt_pk_bf16_f32 v45, v32, v33
	v_lshlrev_b32_e32 v42, 1, v42
	global_store_dwordx2 v42, v[44:45], s[4:5] sc1
.LBB0_409:
	s_waitcnt vmcnt(3)
	v_lshlrev_b32_e32 v42, 16, v98
	v_and_b32_e32 v43, 0xffff0000, v98
	v_lshlrev_b32_e32 v44, 16, v99
	v_and_b32_e32 v45, 0xffff0000, v99
	s_waitcnt lgkmcnt(3)
	v_pk_mul_f32 v[40:41], v[72:73], v[40:41]
	v_pk_mul_f32 v[38:39], v[70:71], v[38:39]
	v_pk_fma_f32 v[40:41], v[40:41], v[14:15], v[44:45] op_sel_hi:[1,0,1]
	v_pk_fma_f32 v[38:39], v[38:39], v[14:15], v[42:43] op_sel_hi:[1,0,1]
	s_and_b64 vcc, exec, s[42:43]
	v_add_u32_e32 v42, 0x46000, v157
	s_cbranch_vccnz .LBB0_465
	v_lshlrev_b32_e32 v43, 2, v42
	global_store_dwordx4 v43, v[38:41], s[8:9] sc1
	s_cbranch_execnz .LBB0_412
.LBB0_411:
	v_cvt_pk_bf16_f32 v44, v38, v39
	v_cvt_pk_bf16_f32 v45, v40, v41
	v_lshlrev_b32_e32 v42, 1, v42
	global_store_dwordx2 v42, v[44:45], s[4:5] sc1
.LBB0_412:
	s_waitcnt vmcnt(2)
	v_lshlrev_b32_e32 v42, 16, v96
	v_and_b32_e32 v43, 0xffff0000, v96
	v_lshlrev_b32_e32 v44, 16, v97
	v_and_b32_e32 v45, 0xffff0000, v97
	s_waitcnt lgkmcnt(2)
	v_pk_mul_f32 v[36:37], v[72:73], v[36:37]
	v_pk_mul_f32 v[34:35], v[70:71], v[34:35]
	v_pk_fma_f32 v[36:37], v[36:37], v[14:15], v[44:45] op_sel:[0,1,0]
	v_pk_fma_f32 v[34:35], v[34:35], v[14:15], v[42:43] op_sel:[0,1,0]
	s_and_b64 vcc, exec, s[42:43]
	v_add_u32_e32 v14, 0x46800, v157
	s_cbranch_vccnz .LBB0_466
	v_lshlrev_b32_e32 v15, 2, v14
	global_store_dwordx4 v15, v[34:37], s[8:9] sc1
	s_cbranch_execnz .LBB0_415
.LBB0_414:
	v_cvt_pk_bf16_f32 v42, v34, v35
	v_cvt_pk_bf16_f32 v43, v36, v37
	v_lshlrev_b32_e32 v14, 1, v14
	global_store_dwordx2 v14, v[42:43], s[4:5] sc1
.LBB0_415:
	s_waitcnt vmcnt(1)
	v_lshlrev_b32_e32 v14, 16, v94
	v_and_b32_e32 v15, 0xffff0000, v94
	v_lshlrev_b32_e32 v42, 16, v95
	v_and_b32_e32 v43, 0xffff0000, v95
	s_waitcnt lgkmcnt(1)
	v_pk_mul_f32 v[28:29], v[72:73], v[28:29]
	v_pk_mul_f32 v[26:27], v[70:71], v[26:27]
	v_pk_fma_f32 v[28:29], v[28:29], v[16:17], v[42:43] op_sel_hi:[1,0,1]
	v_pk_fma_f32 v[26:27], v[26:27], v[16:17], v[14:15] op_sel_hi:[1,0,1]
	s_and_b64 vcc, exec, s[42:43]
	v_add_u32_e32 v14, 0x47000, v157
	s_cbranch_vccnz .LBB0_467
	v_lshlrev_b32_e32 v15, 2, v14
	global_store_dwordx4 v15, v[26:29], s[8:9] sc1
	s_cbranch_execnz .LBB0_418
.LBB0_417:
	v_cvt_pk_bf16_f32 v42, v26, v27
	v_cvt_pk_bf16_f32 v43, v28, v29
	v_lshlrev_b32_e32 v14, 1, v14
	global_store_dwordx2 v14, v[42:43], s[4:5] sc1
.LBB0_418:
	s_waitcnt vmcnt(0)
	v_lshlrev_b32_e32 v14, 16, v2
	v_and_b32_e32 v15, 0xffff0000, v2
	v_lshlrev_b32_e32 v2, 16, v3
	v_and_b32_e32 v3, 0xffff0000, v3
	s_waitcnt lgkmcnt(0)
	v_pk_mul_f32 v[20:21], v[72:73], v[20:21]
	v_pk_mul_f32 v[18:19], v[70:71], v[18:19]
	v_mov_b32_e32 v42, v17
	v_pk_fma_f32 v[16:17], v[20:21], v[42:43], v[2:3] op_sel_hi:[1,0,1]
	v_pk_fma_f32 v[14:15], v[18:19], v[42:43], v[14:15] op_sel_hi:[1,0,1]
	s_and_b64 vcc, exec, s[42:43]
	v_add_u32_e32 v2, 0x47800, v157
	s_cbranch_vccnz .LBB0_468
	v_lshlrev_b32_e32 v3, 2, v2
	global_store_dwordx4 v3, v[14:17], s[8:9] sc1
	s_cbranch_execnz .LBB0_421
.LBB0_420:
	v_cvt_pk_bf16_f32 v18, v14, v15
	v_cvt_pk_bf16_f32 v19, v16, v17
	v_lshlrev_b32_e32 v2, 1, v2
	global_store_dwordx2 v2, v[18:19], s[4:5] sc1

; #define LAS __attribute__((address_space(3)))
;     __device__ __forceinline__ HT hload(unsigned eoff) const { const u32x2 a = *(const u32x2*)((const char*)hi + eoff * 2u); const u32x2 b = *(const u32x2*)((const char*)lo + eoff * 2u); return (u32x4){a.x, a.y, b.x, b.y}; }
;     __device__ __forceinline__ void fused(f32x4 (&acc)[2][2][4][2], const Unit& u, int wr, int wc, int fr, int fq, LAS unsigned char* lds, int wid, int lane) const {
;     ...
;         const f32x4 g1q = *(const f32x4*)(g1 + u.pn * BM + 4 * lane);
; #pragma unroll
;         for (int ai = 0; ai < 2; ++ai) {
;             if (ai == 1) {
; #pragma unroll
;             for (int m = 0; m < 4; ++m)
; #pragma unroll
;                 for (int bj = 0; bj < 2; ++bj)
; #pragma unroll
;                     for (int n = 0; n < 2; ++n) { const int r = wr * 64 + m * 16 + fr, c16 = 32 * bj + 8 * wc + 4 * n + fq;
;                         *(LAS f32x4*)(lds + r * 1024 + ((c16 ^ (r & 15)) << 4)) = acc[1][bj][m][n]; }
;             }
;             asm volatile("s_waitcnt lgkmcnt(0)" ::: "memory"); __builtin_amdgcn_s_barrier(); asm volatile("" ::: "memory");
;             if (ai == 0) {
;                 asm volatile("" :: "v"(H[0]), "v"(H[1]), "v"(H[2]), "v"(H[3]), "v"(H[4]), "v"(H[5]), "v"(H[6]), "v"(H[7]), "v"(H[8]), "v"(H[9]), "v"(H[10]), "v"(H[11]), "v"(H[12]), "v"(H[13]), "v"(H[14]), "v"(H[15]));
; #pragma unroll
;                 for (int j = 0; j < 16; ++j) H2[j] = hload(rbase + (unsigned)((HALF + j) * D));
;             }
;             float sqt = 0.f;
;     ...
;             if (ai == 0) EN_ROWS(4); else EN_ROWS(8);
.LBB0_1068:
	s_or_b64 exec, exec, s[16:17]
	v_readlane_b32 s16, v254, 37
	v_readlane_b32 s17, v254, 38
	s_lshl_b32 s14, s50, 4
	s_lshl_b64 s[16:17], s[16:17], 2
	s_add_u32 s10, s10, s16
	s_addc_u32 s11, s11, s17
	s_add_u32 s8, s8, 0x100000
	s_addc_u32 s9, s9, 0
	s_ashr_i32 s5, s4, 31
	s_lshl_b64 s[4:5], s[4:5], 2
	s_add_u32 s4, s10, s4
	s_addc_u32 s5, s11, s5
	v_lshlrev_b32_e32 v2, 2, v98
	v_mov_b32_e32 v3, v5
	v_lshl_add_u64 v[2:3], s[4:5], 0, v[2:3]
	s_movk_i32 s4, 0x2000
	v_add_co_u32_e32 v2, vcc, s4, v2
	v_add_u32_e32 v74, 0x80000, v4
	s_nop 0
	v_addc_co_u32_e32 v3, vcc, 0, v3, vcc
	v_mov_b32_e32 v75, v5
	global_load_dwordx4 v[70:73], v[2:3], off
	s_waitcnt lgkmcnt(0)
	s_barrier
	s_waitcnt vmcnt(0)
	v_lshl_add_u64 v[134:135], s[12:13], 0, v[74:75]
	global_load_dwordx2 v[142:143], v74, s[12:13]
	v_add_u32_e32 v74, 0x81000, v4
	v_lshl_add_u64 v[130:131], s[12:13], 0, v[74:75]
	global_load_dwordx2 v[138:139], v74, s[12:13]
	v_add_u32_e32 v74, 0x82000, v4
	v_lshl_add_u64 v[122:123], s[12:13], 0, v[74:75]
	global_load_dwordx2 v[140:141], v74, s[12:13]
	v_add_u32_e32 v74, 0x83000, v4
	v_lshl_add_u64 v[118:119], s[12:13], 0, v[74:75]
	global_load_dwordx2 v[132:133], v74, s[12:13]
	v_add_u32_e32 v74, 0x84000, v4
	v_lshl_add_u64 v[116:117], s[12:13], 0, v[74:75]
	global_load_dwordx2 v[128:129], v74, s[12:13]
	v_add_u32_e32 v74, 0x85000, v4
	v_lshl_add_u64 v[110:111], s[12:13], 0, v[74:75]
	global_load_dwordx2 v[120:121], v74, s[12:13]
	v_add_u32_e32 v74, 0x86000, v4
	v_lshl_add_u64 v[108:109], s[12:13], 0, v[74:75]
	global_load_dwordx2 v[126:127], v74, s[12:13]
	v_add_u32_e32 v74, 0x87000, v4
	v_lshl_add_u64 v[106:107], s[12:13], 0, v[74:75]
	global_load_dwordx2 v[114:115], v74, s[12:13]
	v_add_u32_e32 v74, 0x88000, v4
	v_lshl_add_u64 v[98:99], s[12:13], 0, v[74:75]
	global_load_dwordx2 v[104:105], v74, s[12:13]
	v_add_u32_e32 v74, 0x89000, v4
	v_lshl_add_u64 v[94:95], s[12:13], 0, v[74:75]
	global_load_dwordx2 v[100:101], v74, s[12:13]
	v_add_u32_e32 v74, 0x8a000, v4
	v_lshl_add_u64 v[88:89], s[12:13], 0, v[74:75]
	global_load_dwordx2 v[102:103], v74, s[12:13]
	v_add_u32_e32 v74, 0x8b000, v4
	v_lshl_add_u64 v[84:85], s[12:13], 0, v[74:75]
	global_load_dwordx2 v[96:97], v74, s[12:13]
	v_add_u32_e32 v74, 0x8c000, v4
	v_lshl_add_u64 v[80:81], s[12:13], 0, v[74:75]
	global_load_dwordx2 v[92:93], v74, s[12:13]
	v_add_u32_e32 v74, 0x8d000, v4
	v_lshl_add_u64 v[78:79], s[12:13], 0, v[74:75]
	global_load_dwordx2 v[86:87], v74, s[12:13]
	v_add_u32_e32 v74, 0x8e000, v4
	v_add_u32_e32 v4, 0x8f000, v4
	global_load_dwordx2 v[90:91], v74, s[12:13]
	global_load_dwordx2 v[82:83], v4, s[12:13]
	s_lshl_b32 s4, s50, 14
	s_lshl_b32 s10, s50, 6
	s_add_i32 s5, 0, 0x21400
	v_lshl_add_u64 v[76:77], s[12:13], 0, v[74:75]
	v_lshl_add_u64 v[74:75], s[12:13], 0, v[4:5]
	s_add_i32 s4, s4, 0
	v_lshlrev_b32_e32 v3, 4, v216
	s_add_i32 s12, s5, s10
	v_add_u32_e32 v4, s4, v3
	v_mov_b32_e32 v221, s12
	ds_read_b128 v[224:227], v4
	ds_read_b128 v[228:231], v221
	s_add_i32 s10, s4, 0x400
	v_xor_b32_e32 v221, 16, v3
	v_add_u32_e32 v221, s10, v221
	s_add_i32 s10, s4, 0x800
	v_xor_b32_e32 v222, 32, v3
	v_add_u32_e32 v222, s10, v222
	s_add_i32 s10, s4, 0xc00
	v_xor_b32_e32 v223, 48, v3
	v_add_u32_e32 v223, s10, v223
	ds_read_b128 v[236:239], v221
	ds_read_b128 v[240:243], v222
	ds_read_b128 v[244:247], v223
	s_add_i32 s7, s7, s14
	v_add_u32_e32 v2, s7, v216
	s_ashr_i32 s7, s6, 31
	v_lshlrev_b32_e32 v248, 16, v194
	v_and_b32_e32 v249, 0xffff0000, v194
	s_waitcnt lgkmcnt(4)
	v_pk_mul_f32 v[224:225], v[70:71], v[224:225]
	v_lshlrev_b32_e32 v194, 16, v195
	v_and_b32_e32 v195, 0xffff0000, v195
	v_pk_mul_f32 v[226:227], v[72:73], v[226:227]
	s_waitcnt lgkmcnt(3)
	v_pk_fma_f32 v[224:225], v[224:225], v[228:229], v[248:249] op_sel_hi:[1,0,1]
	v_pk_fma_f32 v[194:195], v[226:227], v[228:229], v[194:195] op_sel_hi:[1,0,1]
	v_mul_f32_e32 v226, v225, v225
	v_fmac_f32_e32 v226, v224, v224
	v_mul_f32_e32 v227, v195, v195
	v_cvt_pk_bf16_f32 v224, v224, v225
	v_cvt_pk_bf16_f32 v225, v194, v195
	v_fmac_f32_e32 v227, v194, v194
	global_store_dwordx2 v[214:215], v[224:225], off sc1
	v_lshlrev_b32_e32 v194, 16, v190
	v_and_b32_e32 v195, 0xffff0000, v190
	s_waitcnt lgkmcnt(2)
	v_pk_mul_f32 v[224:225], v[70:71], v[236:237]
	v_lshlrev_b32_e32 v190, 16, v191
	v_and_b32_e32 v191, 0xffff0000, v191
	v_pk_mul_f32 v[214:215], v[72:73], v[238:239]
	v_pk_fma_f32 v[194:195], v[224:225], v[228:229], v[194:195] op_sel:[0,1,0]
	v_pk_fma_f32 v[190:191], v[214:215], v[228:229], v[190:191] op_sel:[0,1,0]
	v_mul_f32_e32 v214, v195, v195
	v_fmac_f32_e32 v214, v194, v194
	v_mul_f32_e32 v215, v191, v191
	v_cvt_pk_bf16_f32 v194, v194, v195
	v_cvt_pk_bf16_f32 v195, v190, v191
	v_fmac_f32_e32 v215, v190, v190
	global_store_dwordx2 v[212:213], v[194:195], off sc1
	v_lshlrev_b32_e32 v190, 16, v188
	v_and_b32_e32 v191, 0xffff0000, v188
	v_lshlrev_b32_e32 v188, 16, v189
	v_and_b32_e32 v189, 0xffff0000, v189
	s_waitcnt lgkmcnt(1)
	v_pk_mul_f32 v[194:195], v[72:73], v[242:243]
	v_pk_mul_f32 v[212:213], v[70:71], v[240:241]
	v_pk_fma_f32 v[188:189], v[194:195], v[230:231], v[188:189] op_sel_hi:[1,0,1]
	v_pk_fma_f32 v[190:191], v[212:213], v[230:231], v[190:191] op_sel_hi:[1,0,1]
	v_mul_f32_e32 v195, v189, v189
	v_mul_f32_e32 v194, v191, v191
	v_fmac_f32_e32 v194, v190, v190
	v_fmac_f32_e32 v195, v188, v188
	v_cvt_pk_bf16_f32 v190, v190, v191
	v_cvt_pk_bf16_f32 v191, v188, v189
	v_add_f32_e32 v212, v194, v195
	global_store_dwordx2 v[196:197], v[190:191], off sc1
	v_lshlrev_b32_e32 v188, 16, v186
	v_and_b32_e32 v189, 0xffff0000, v186
	v_lshlrev_b32_e32 v186, 16, v187
	v_and_b32_e32 v187, 0xffff0000, v187
	s_waitcnt lgkmcnt(0)
;     __device__ __forceinline__ void fused(f32x4 (&acc)[2][2][4][2], const Unit& u, int wr, int wc, int fr, int fq, LAS unsigned char* lds, int wid, int lane) const {
;     ...
;             if (ai == 0) EN_ROWS(4); else EN_ROWS(8);
	v_pk_mul_f32 v[190:191], v[72:73], v[246:247]
	v_pk_mul_f32 v[194:195], v[70:71], v[244:245]
	v_mov_b32_e32 v196, v231
	v_pk_fma_f32 v[186:187], v[190:191], v[196:197], v[186:187] op_sel_hi:[1,0,1]
	v_pk_fma_f32 v[188:189], v[194:195], v[196:197], v[188:189] op_sel_hi:[1,0,1]
	v_add_f32_e32 v226, v226, v227
	v_mul_f32_e32 v190, v189, v189
	v_mul_f32_e32 v191, v187, v187
	v_fmac_f32_e32 v190, v188, v188
	v_fmac_f32_e32 v191, v186, v186
	v_cvt_pk_bf16_f32 v188, v188, v189
	v_cvt_pk_bf16_f32 v189, v186, v187
	v_add_f32_dpp v186, v226, v226 quad_perm:[1,0,3,2] row_mask:0xf bank_mask:0xf bound_ctrl:1
	v_add_f32_e32 v214, v214, v215
	v_add_f32_e32 v190, v190, v191
	v_add_f32_dpp v186, v186, v186 quad_perm:[2,3,0,1] row_mask:0xf bank_mask:0xf bound_ctrl:1
	v_add_f32_dpp v187, v214, v214 quad_perm:[1,0,3,2] row_mask:0xf bank_mask:0xf bound_ctrl:1
	global_store_dwordx2 v[192:193], v[188:189], off sc1
	v_add_f32_dpp v186, v186, v186 row_half_mirror row_mask:0xf bank_mask:0xf bound_ctrl:1
	v_add_f32_dpp v187, v187, v187 quad_perm:[2,3,0,1] row_mask:0xf bank_mask:0xf bound_ctrl:1
	v_add_f32_dpp v188, v212, v212 quad_perm:[1,0,3,2] row_mask:0xf bank_mask:0xf bound_ctrl:1
	v_add_f32_dpp v186, v186, v186 row_mirror row_mask:0xf bank_mask:0xf bound_ctrl:1
	v_add_f32_dpp v189, v190, v190 quad_perm:[1,0,3,2] row_mask:0xf bank_mask:0xf bound_ctrl:1
	v_add_f32_dpp v187, v187, v187 row_half_mirror row_mask:0xf bank_mask:0xf bound_ctrl:1
	v_mov_b32_e32 v190, v186
	v_add_f32_dpp v188, v188, v188 quad_perm:[2,3,0,1] row_mask:0xf bank_mask:0xf bound_ctrl:1
	v_add_f32_dpp v187, v187, v187 row_mirror row_mask:0xf bank_mask:0xf bound_ctrl:1
	v_permlane16_swap_b32_e32 v186, v190
	v_add_f32_dpp v188, v188, v188 row_half_mirror row_mask:0xf bank_mask:0xf bound_ctrl:1
	v_add_f32_e32 v190, v186, v190
	v_mov_b32_e32 v186, v187
	v_add_f32_dpp v189, v189, v189 quad_perm:[2,3,0,1] row_mask:0xf bank_mask:0xf bound_ctrl:1
	v_add_f32_dpp v188, v188, v188 row_mirror row_mask:0xf bank_mask:0xf bound_ctrl:1
	v_permlane16_swap_b32_e32 v187, v186
	v_add_f32_dpp v189, v189, v189 row_half_mirror row_mask:0xf bank_mask:0xf bound_ctrl:1
	v_add_f32_e32 v191, v187, v186
	v_mov_b32_e32 v186, v188
	v_add_f32_dpp v189, v189, v189 row_mirror row_mask:0xf bank_mask:0xf bound_ctrl:1
	s_nop 0
	v_permlane16_swap_b32_e32 v188, v186
	v_add_f32_e32 v192, v188, v186
	v_mov_b32_e32 v186, v189
	s_or_b32 s10, s14, 4
	s_nop 0
	v_permlane16_swap_b32_e32 v189, v186
	s_lshl_b32 s11, s10, 10
	s_lshl_b32 s10, s10, 2
	v_add_f32_e32 v194, v189, v186
	s_add_i32 s11, s11, 0
	v_xor_b32_e32 v186, 64, v3
	s_add_i32 s15, s5, s10
	v_add_u32_e32 v186, s11, v186
	v_mov_b32_e32 v187, s15
	ds_read_b128 v[212:215], v186
	ds_read_b128 v[224:227], v187
	s_add_i32 s10, s4, 0x1400
	v_xor_b32_e32 v187, 0x50, v3
	v_add_u32_e32 v187, s10, v187
	s_add_i32 s10, s4, 0x1800
	v_xor_b32_e32 v188, 0x60, v3
	v_add_u32_e32 v188, s10, v188
	s_add_i32 s10, s4, 0x1c00
	v_xor_b32_e32 v189, 0x70, v3
	ds_read_b128 v[228:231], v187
	ds_read_b128 v[236:239], v188
	v_add_u32_e32 v189, s10, v189
	ds_read_b128 v[240:243], v189
	v_mov_b32_e32 v193, v190
	v_mov_b32_e32 v195, v191
	v_mov_b32_e32 v196, v192
	v_mov_b32_e32 v197, v194
	v_permlane32_swap_b32_e32 v190, v193
	v_permlane32_swap_b32_e32 v191, v195
	v_permlane32_swap_b32_e32 v192, v196
	v_permlane32_swap_b32_e32 v194, v197
	v_cmp_eq_u32_e32 vcc, 1, v216
	v_cmp_eq_u32_e64 s[42:43], 2, v216
	v_cmp_eq_u32_e64 s[44:45], 3, v216
	v_lshlrev_b32_e32 v244, 16, v176
	v_and_b32_e32 v245, 0xffff0000, v176
	s_waitcnt lgkmcnt(4)
	v_pk_mul_f32 v[212:213], v[70:71], v[212:213]
	v_lshlrev_b32_e32 v176, 16, v177
	v_and_b32_e32 v177, 0xffff0000, v177
	v_pk_mul_f32 v[214:215], v[72:73], v[214:215]
	s_waitcnt lgkmcnt(3)
	v_pk_fma_f32 v[212:213], v[212:213], v[224:225], v[244:245] op_sel_hi:[1,0,1]
	v_pk_fma_f32 v[176:177], v[214:215], v[224:225], v[176:177] op_sel_hi:[1,0,1]
	v_mul_f32_e32 v214, v213, v213
	v_fmac_f32_e32 v214, v212, v212
	v_mul_f32_e32 v215, v177, v177
	v_cvt_pk_bf16_f32 v212, v212, v213
	v_cvt_pk_bf16_f32 v213, v176, v177
	v_fmac_f32_e32 v215, v176, v176
	global_store_dwordx2 v[184:185], v[212:213], off sc1
	v_lshlrev_b32_e32 v176, 16, v174
	v_and_b32_e32 v177, 0xffff0000, v174
	s_waitcnt lgkmcnt(2)
	v_pk_mul_f32 v[212:213], v[70:71], v[228:229]
	v_lshlrev_b32_e32 v174, 16, v175
	v_and_b32_e32 v175, 0xffff0000, v175
	v_pk_mul_f32 v[184:185], v[72:73], v[230:231]
	v_pk_fma_f32 v[176:177], v[212:213], v[224:225], v[176:177] op_sel:[0,1,0]
	v_pk_fma_f32 v[174:175], v[184:185], v[224:225], v[174:175] op_sel:[0,1,0]
	v_mul_f32_e32 v184, v177, v177
	v_fmac_f32_e32 v184, v176, v176
	v_mul_f32_e32 v185, v175, v175
	v_cvt_pk_bf16_f32 v176, v176, v177
	v_cvt_pk_bf16_f32 v177, v174, v175
	v_fmac_f32_e32 v185, v174, v174
	global_store_dwordx2 v[182:183], v[176:177], off sc1
	v_lshlrev_b32_e32 v174, 16, v172
	v_and_b32_e32 v175, 0xffff0000, v172
	v_lshlrev_b32_e32 v172, 16, v173
	v_and_b32_e32 v173, 0xffff0000, v173
	s_waitcnt lgkmcnt(1)
	v_pk_mul_f32 v[176:177], v[72:73], v[238:239]
	v_pk_mul_f32 v[182:183], v[70:71], v[236:237]
	v_pk_fma_f32 v[172:173], v[176:177], v[226:227], v[172:173] op_sel_hi:[1,0,1]
	v_pk_fma_f32 v[174:175], v[182:183], v[226:227], v[174:175] op_sel_hi:[1,0,1]
	v_mul_f32_e32 v177, v173, v173
	v_mul_f32_e32 v176, v175, v175
	v_fmac_f32_e32 v176, v174, v174
	v_fmac_f32_e32 v177, v172, v172
	v_cvt_pk_bf16_f32 v174, v174, v175
	v_cvt_pk_bf16_f32 v175, v172, v173
	v_add_f32_e32 v182, v176, v177
	global_store_dwordx2 v[180:181], v[174:175], off sc1
	v_lshlrev_b32_e32 v172, 16, v170
	v_and_b32_e32 v173, 0xffff0000, v170
	v_lshlrev_b32_e32 v170, 16, v171
	v_and_b32_e32 v171, 0xffff0000, v171
	s_waitcnt lgkmcnt(0)
;     __device__ __forceinline__ void fused(f32x4 (&acc)[2][2][4][2], const Unit& u, int wr, int wc, int fr, int fq, LAS unsigned char* lds, int wid, int lane) const {
;     ...
;             if (ai == 0) EN_ROWS(4); else EN_ROWS(8);
	v_pk_mul_f32 v[174:175], v[72:73], v[242:243]
	v_pk_mul_f32 v[176:177], v[70:71], v[240:241]
	v_mov_b32_e32 v180, v227
	v_pk_fma_f32 v[170:171], v[174:175], v[180:181], v[170:171] op_sel_hi:[1,0,1]
	v_pk_fma_f32 v[172:173], v[176:177], v[180:181], v[172:173] op_sel_hi:[1,0,1]
	v_add_f32_e32 v214, v214, v215
	v_mul_f32_e32 v174, v173, v173
	v_mul_f32_e32 v175, v171, v171
	v_fmac_f32_e32 v174, v172, v172
	v_fmac_f32_e32 v175, v170, v170
	v_cvt_pk_bf16_f32 v172, v172, v173
	v_cvt_pk_bf16_f32 v173, v170, v171
	v_add_f32_dpp v170, v214, v214 quad_perm:[1,0,3,2] row_mask:0xf bank_mask:0xf bound_ctrl:1
	v_add_f32_e32 v184, v184, v185
	v_add_f32_e32 v174, v174, v175
	v_add_f32_dpp v170, v170, v170 quad_perm:[2,3,0,1] row_mask:0xf bank_mask:0xf bound_ctrl:1
	v_add_f32_dpp v171, v184, v184 quad_perm:[1,0,3,2] row_mask:0xf bank_mask:0xf bound_ctrl:1
	global_store_dwordx2 v[178:179], v[172:173], off sc1
	v_add_f32_dpp v170, v170, v170 row_half_mirror row_mask:0xf bank_mask:0xf bound_ctrl:1
	v_add_f32_dpp v171, v171, v171 quad_perm:[2,3,0,1] row_mask:0xf bank_mask:0xf bound_ctrl:1
	v_add_f32_dpp v172, v182, v182 quad_perm:[1,0,3,2] row_mask:0xf bank_mask:0xf bound_ctrl:1
	v_add_f32_dpp v170, v170, v170 row_mirror row_mask:0xf bank_mask:0xf bound_ctrl:1
	v_add_f32_dpp v173, v174, v174 quad_perm:[1,0,3,2] row_mask:0xf bank_mask:0xf bound_ctrl:1
	v_add_f32_dpp v171, v171, v171 row_half_mirror row_mask:0xf bank_mask:0xf bound_ctrl:1
	v_mov_b32_e32 v174, v170
	v_add_f32_dpp v172, v172, v172 quad_perm:[2,3,0,1] row_mask:0xf bank_mask:0xf bound_ctrl:1
	v_add_f32_dpp v171, v171, v171 row_mirror row_mask:0xf bank_mask:0xf bound_ctrl:1
	v_permlane16_swap_b32_e32 v170, v174
	v_add_f32_dpp v172, v172, v172 row_half_mirror row_mask:0xf bank_mask:0xf bound_ctrl:1
	v_add_f32_e32 v174, v170, v174
	v_mov_b32_e32 v170, v171
	v_add_f32_dpp v173, v173, v173 quad_perm:[2,3,0,1] row_mask:0xf bank_mask:0xf bound_ctrl:1
	v_add_f32_dpp v172, v172, v172 row_mirror row_mask:0xf bank_mask:0xf bound_ctrl:1
	v_permlane16_swap_b32_e32 v171, v170
	v_add_f32_dpp v173, v173, v173 row_half_mirror row_mask:0xf bank_mask:0xf bound_ctrl:1
	v_add_f32_e32 v175, v171, v170
	v_mov_b32_e32 v170, v172
	v_add_f32_dpp v173, v173, v173 row_mirror row_mask:0xf bank_mask:0xf bound_ctrl:1
	s_nop 0
	v_permlane16_swap_b32_e32 v172, v170
	v_add_f32_e32 v176, v172, v170
	v_mov_b32_e32 v170, v173
	s_or_b32 s10, s14, 8
	s_nop 0
	v_permlane16_swap_b32_e32 v173, v170
	s_lshl_b32 s11, s10, 10
	s_lshl_b32 s10, s10, 2
	v_add_f32_e32 v178, v173, v170
	s_add_i32 s11, s11, 0
	v_xor_b32_e32 v170, 0x80, v3
	s_add_i32 s13, s5, s10
	v_add_u32_e32 v170, s11, v170
	v_mov_b32_e32 v171, s13
	ds_read_b128 v[182:185], v170
	ds_read_b128 v[212:215], v171
	s_add_i32 s10, s4, 0x2400
	v_xor_b32_e32 v171, 0x90, v3
	v_add_u32_e32 v171, s10, v171
	s_add_i32 s10, s4, 0x2800
	v_xor_b32_e32 v172, 0xa0, v3
	v_add_u32_e32 v172, s10, v172
	s_add_i32 s10, s4, 0x2c00
	v_xor_b32_e32 v173, 0xb0, v3
	ds_read_b128 v[224:227], v171
	ds_read_b128 v[228:231], v172
	v_add_u32_e32 v173, s10, v173
	ds_read_b128 v[236:239], v173
	v_mov_b32_e32 v177, v174
	v_mov_b32_e32 v179, v175
	v_mov_b32_e32 v180, v176
	v_mov_b32_e32 v181, v178
	v_permlane32_swap_b32_e32 v174, v177
	v_permlane32_swap_b32_e32 v175, v179
	v_permlane32_swap_b32_e32 v176, v180
	v_permlane32_swap_b32_e32 v178, v181
	v_cmp_eq_u32_e64 s[46:47], 4, v216
	v_cmp_eq_u32_e64 s[48:49], 5, v216
	v_cmp_eq_u32_e64 s[50:51], 6, v216
	v_cmp_eq_u32_e64 s[52:53], 7, v216
	v_lshlrev_b32_e32 v240, 16, v160
	v_and_b32_e32 v241, 0xffff0000, v160
	s_waitcnt lgkmcnt(4)
	v_pk_mul_f32 v[182:183], v[70:71], v[182:183]
	v_lshlrev_b32_e32 v160, 16, v161
	v_and_b32_e32 v161, 0xffff0000, v161
	v_pk_mul_f32 v[184:185], v[72:73], v[184:185]
	s_waitcnt lgkmcnt(3)
	v_pk_fma_f32 v[182:183], v[182:183], v[212:213], v[240:241] op_sel_hi:[1,0,1]
	v_pk_fma_f32 v[160:161], v[184:185], v[212:213], v[160:161] op_sel_hi:[1,0,1]
	v_mul_f32_e32 v184, v183, v183
	v_fmac_f32_e32 v184, v182, v182
	v_mul_f32_e32 v185, v161, v161
	v_cvt_pk_bf16_f32 v182, v182, v183
	v_cvt_pk_bf16_f32 v183, v160, v161
	v_fmac_f32_e32 v185, v160, v160
	global_store_dwordx2 v[168:169], v[182:183], off sc1
	v_lshlrev_b32_e32 v160, 16, v158
	v_and_b32_e32 v161, 0xffff0000, v158
	s_waitcnt lgkmcnt(2)
	v_pk_mul_f32 v[182:183], v[70:71], v[224:225]
	v_lshlrev_b32_e32 v158, 16, v159
	v_and_b32_e32 v159, 0xffff0000, v159
	v_pk_mul_f32 v[168:169], v[72:73], v[226:227]
	v_pk_fma_f32 v[160:161], v[182:183], v[212:213], v[160:161] op_sel:[0,1,0]
	v_pk_fma_f32 v[158:159], v[168:169], v[212:213], v[158:159] op_sel:[0,1,0]
	v_mul_f32_e32 v168, v161, v161
	v_fmac_f32_e32 v168, v160, v160
	v_mul_f32_e32 v169, v159, v159
	v_cvt_pk_bf16_f32 v160, v160, v161
	v_cvt_pk_bf16_f32 v161, v158, v159
	v_fmac_f32_e32 v169, v158, v158
	global_store_dwordx2 v[166:167], v[160:161], off sc1
	v_lshlrev_b32_e32 v158, 16, v156
	v_and_b32_e32 v159, 0xffff0000, v156
	v_lshlrev_b32_e32 v156, 16, v157
	v_and_b32_e32 v157, 0xffff0000, v157
	s_waitcnt lgkmcnt(1)
	v_pk_mul_f32 v[160:161], v[72:73], v[230:231]
	v_pk_mul_f32 v[166:167], v[70:71], v[228:229]
	v_pk_fma_f32 v[156:157], v[160:161], v[214:215], v[156:157] op_sel_hi:[1,0,1]
	v_pk_fma_f32 v[158:159], v[166:167], v[214:215], v[158:159] op_sel_hi:[1,0,1]
	v_mul_f32_e32 v161, v157, v157
	v_mul_f32_e32 v160, v159, v159
	v_fmac_f32_e32 v160, v158, v158
	v_fmac_f32_e32 v161, v156, v156
	v_cvt_pk_bf16_f32 v158, v158, v159
	v_cvt_pk_bf16_f32 v159, v156, v157
	v_add_f32_e32 v166, v160, v161
	global_store_dwordx2 v[164:165], v[158:159], off sc1
	v_lshlrev_b32_e32 v156, 16, v154
	v_and_b32_e32 v157, 0xffff0000, v154
	v_lshlrev_b32_e32 v154, 16, v155
	v_and_b32_e32 v155, 0xffff0000, v155
	s_waitcnt lgkmcnt(0)
;     __device__ __forceinline__ void fused(f32x4 (&acc)[2][2][4][2], const Unit& u, int wr, int wc, int fr, int fq, LAS unsigned char* lds, int wid, int lane) const {
;     ...
;             if (ai == 0) EN_ROWS(4); else EN_ROWS(8);
	v_pk_mul_f32 v[158:159], v[72:73], v[238:239]
	v_pk_mul_f32 v[160:161], v[70:71], v[236:237]
	v_mov_b32_e32 v164, v215
	v_pk_fma_f32 v[154:155], v[158:159], v[164:165], v[154:155] op_sel_hi:[1,0,1]
	v_pk_fma_f32 v[156:157], v[160:161], v[164:165], v[156:157] op_sel_hi:[1,0,1]
	v_add_f32_e32 v184, v184, v185
	v_mul_f32_e32 v158, v157, v157
	v_mul_f32_e32 v159, v155, v155
	v_fmac_f32_e32 v158, v156, v156
	v_fmac_f32_e32 v159, v154, v154
	v_cvt_pk_bf16_f32 v156, v156, v157
	v_cvt_pk_bf16_f32 v157, v154, v155
	v_add_f32_dpp v154, v184, v184 quad_perm:[1,0,3,2] row_mask:0xf bank_mask:0xf bound_ctrl:1
	v_add_f32_e32 v168, v168, v169
	v_add_f32_e32 v158, v158, v159
	v_add_f32_dpp v154, v154, v154 quad_perm:[2,3,0,1] row_mask:0xf bank_mask:0xf bound_ctrl:1
	v_add_f32_dpp v155, v168, v168 quad_perm:[1,0,3,2] row_mask:0xf bank_mask:0xf bound_ctrl:1
	global_store_dwordx2 v[162:163], v[156:157], off sc1
	v_add_f32_dpp v154, v154, v154 row_half_mirror row_mask:0xf bank_mask:0xf bound_ctrl:1
	v_add_f32_dpp v155, v155, v155 quad_perm:[2,3,0,1] row_mask:0xf bank_mask:0xf bound_ctrl:1
	v_add_f32_dpp v156, v166, v166 quad_perm:[1,0,3,2] row_mask:0xf bank_mask:0xf bound_ctrl:1
	v_add_f32_dpp v154, v154, v154 row_mirror row_mask:0xf bank_mask:0xf bound_ctrl:1
	v_add_f32_dpp v157, v158, v158 quad_perm:[1,0,3,2] row_mask:0xf bank_mask:0xf bound_ctrl:1
	v_add_f32_dpp v155, v155, v155 row_half_mirror row_mask:0xf bank_mask:0xf bound_ctrl:1
	v_mov_b32_e32 v158, v154
	v_add_f32_dpp v156, v156, v156 quad_perm:[2,3,0,1] row_mask:0xf bank_mask:0xf bound_ctrl:1
	v_add_f32_dpp v155, v155, v155 row_mirror row_mask:0xf bank_mask:0xf bound_ctrl:1
	v_permlane16_swap_b32_e32 v154, v158
	v_add_f32_dpp v156, v156, v156 row_half_mirror row_mask:0xf bank_mask:0xf bound_ctrl:1
	v_add_f32_e32 v158, v154, v158
	v_mov_b32_e32 v154, v155
	v_add_f32_dpp v157, v157, v157 quad_perm:[2,3,0,1] row_mask:0xf bank_mask:0xf bound_ctrl:1
	v_add_f32_dpp v156, v156, v156 row_mirror row_mask:0xf bank_mask:0xf bound_ctrl:1
	v_permlane16_swap_b32_e32 v155, v154
	v_add_f32_dpp v157, v157, v157 row_half_mirror row_mask:0xf bank_mask:0xf bound_ctrl:1
	v_add_f32_e32 v159, v155, v154
	v_mov_b32_e32 v154, v156
	v_add_f32_dpp v157, v157, v157 row_mirror row_mask:0xf bank_mask:0xf bound_ctrl:1
	s_nop 0
	v_permlane16_swap_b32_e32 v156, v154
	v_add_f32_e32 v160, v156, v154
	v_mov_b32_e32 v154, v157
	s_or_b32 s10, s14, 12
	s_nop 0
	v_permlane16_swap_b32_e32 v157, v154
	s_lshl_b32 s11, s10, 10
	s_lshl_b32 s10, s10, 2
	v_add_f32_e32 v162, v157, v154
	s_add_i32 s11, s11, 0
	v_xor_b32_e32 v154, 0xc0, v3
	s_add_i32 s14, s5, s10
	v_add_u32_e32 v154, s11, v154
	v_mov_b32_e32 v155, s14
	ds_read_b128 v[166:169], v154
	ds_read_b128 v[182:185], v155
	s_add_i32 s5, s4, 0x3400
	v_xor_b32_e32 v155, 0xd0, v3
	v_add_u32_e32 v155, s5, v155
	s_add_i32 s5, s4, 0x3800
	v_xor_b32_e32 v156, 0xe0, v3
	s_addk_i32 s4, 0x3c00
	v_xor_b32_e32 v3, 0xf0, v3
	v_add_u32_e32 v156, s5, v156
	ds_read_b128 v[212:215], v155
	ds_read_b128 v[224:227], v156
	v_add_u32_e32 v157, s4, v3
	ds_read_b128 v[228:231], v157
	v_mov_b32_e32 v161, v158
	v_mov_b32_e32 v163, v159
	v_mov_b32_e32 v164, v160
	v_mov_b32_e32 v165, v162
	v_permlane32_swap_b32_e32 v158, v161
	v_permlane32_swap_b32_e32 v159, v163
	v_permlane32_swap_b32_e32 v160, v164
	v_permlane32_swap_b32_e32 v162, v165
	v_cmp_eq_u32_e64 s[54:55], 8, v216
	v_cmp_eq_u32_e64 s[56:57], 9, v216
	v_cmp_eq_u32_e64 s[58:59], 10, v216
	v_cmp_eq_u32_e64 s[60:61], 11, v216
	v_lshlrev_b32_e32 v236, 16, v144
	v_and_b32_e32 v237, 0xffff0000, v144
	s_waitcnt lgkmcnt(4)
	v_pk_mul_f32 v[166:167], v[70:71], v[166:167]
	v_lshlrev_b32_e32 v144, 16, v145
	v_and_b32_e32 v145, 0xffff0000, v145
	v_pk_mul_f32 v[168:169], v[72:73], v[168:169]
	s_waitcnt lgkmcnt(3)
	v_pk_fma_f32 v[166:167], v[166:167], v[182:183], v[236:237] op_sel_hi:[1,0,1]
	v_pk_fma_f32 v[144:145], v[168:169], v[182:183], v[144:145] op_sel_hi:[1,0,1]
	v_mul_f32_e32 v3, v167, v167
	v_fmac_f32_e32 v3, v166, v166
	v_mul_f32_e32 v168, v145, v145
	v_cvt_pk_bf16_f32 v166, v166, v167
	v_cvt_pk_bf16_f32 v167, v144, v145
	v_fmac_f32_e32 v168, v144, v144
	global_store_dwordx2 v[152:153], v[166:167], off sc1
	v_lshlrev_b32_e32 v144, 16, v136
	v_and_b32_e32 v145, 0xffff0000, v136
	s_waitcnt lgkmcnt(2)
	v_pk_mul_f32 v[166:167], v[70:71], v[212:213]
	v_lshlrev_b32_e32 v136, 16, v137
	v_and_b32_e32 v137, 0xffff0000, v137
	v_pk_mul_f32 v[152:153], v[72:73], v[214:215]
	v_pk_fma_f32 v[144:145], v[166:167], v[182:183], v[144:145] op_sel:[0,1,0]
	v_pk_fma_f32 v[136:137], v[152:153], v[182:183], v[136:137] op_sel:[0,1,0]
	v_mul_f32_e32 v152, v145, v145
	v_fmac_f32_e32 v152, v144, v144
	v_mul_f32_e32 v153, v137, v137
	v_cvt_pk_bf16_f32 v144, v144, v145
	v_cvt_pk_bf16_f32 v145, v136, v137
	v_fmac_f32_e32 v153, v136, v136
	global_store_dwordx2 v[150:151], v[144:145], off sc1
	v_lshlrev_b32_e32 v136, 16, v124
	v_and_b32_e32 v137, 0xffff0000, v124
	v_lshlrev_b32_e32 v124, 16, v125
	v_and_b32_e32 v125, 0xffff0000, v125
	s_waitcnt lgkmcnt(1)
	v_pk_mul_f32 v[144:145], v[72:73], v[226:227]
	v_pk_mul_f32 v[150:151], v[70:71], v[224:225]
	v_pk_fma_f32 v[124:125], v[144:145], v[184:185], v[124:125] op_sel_hi:[1,0,1]
	v_pk_fma_f32 v[136:137], v[150:151], v[184:185], v[136:137] op_sel_hi:[1,0,1]
	v_mul_f32_e32 v145, v125, v125
	v_mul_f32_e32 v144, v137, v137
	v_fmac_f32_e32 v144, v136, v136
	v_fmac_f32_e32 v145, v124, v124
	v_cvt_pk_bf16_f32 v136, v136, v137
	v_cvt_pk_bf16_f32 v137, v124, v125
	v_add_f32_e32 v3, v3, v168
	v_add_f32_e32 v150, v144, v145
	global_store_dwordx2 v[148:149], v[136:137], off sc1
	v_lshlrev_b32_e32 v124, 16, v112
	v_and_b32_e32 v125, 0xffff0000, v112
	v_lshlrev_b32_e32 v112, 16, v113
	v_and_b32_e32 v113, 0xffff0000, v113
	s_waitcnt lgkmcnt(0)
;     __device__ __forceinline__ void fused(f32x4 (&acc)[2][2][4][2], const Unit& u, int wr, int wc, int fr, int fq, LAS unsigned char* lds, int wid, int lane) const {
;     ...
;             if (ai == 0) EN_ROWS(4); else EN_ROWS(8);
;     ...
;             if (lane < 16) st2[(size_t)(u.pm * BM + ai * HALF + 16 * wid + lane) * 8 + u.pn] = sqt;
	v_pk_mul_f32 v[136:137], v[72:73], v[230:231]
	v_pk_mul_f32 v[144:145], v[70:71], v[228:229]
	v_mov_b32_e32 v148, v185
	v_pk_fma_f32 v[112:113], v[136:137], v[148:149], v[112:113] op_sel_hi:[1,0,1]
	v_pk_fma_f32 v[124:125], v[144:145], v[148:149], v[124:125] op_sel_hi:[1,0,1]
	v_add_f32_dpp v3, v3, v3 quad_perm:[1,0,3,2] row_mask:0xf bank_mask:0xf bound_ctrl:1
	v_add_f32_e32 v152, v152, v153
	v_mul_f32_e32 v136, v125, v125
	v_mul_f32_e32 v137, v113, v113
	v_add_f32_dpp v3, v3, v3 quad_perm:[2,3,0,1] row_mask:0xf bank_mask:0xf bound_ctrl:1
	v_fmac_f32_e32 v136, v124, v124
	v_fmac_f32_e32 v137, v112, v112
	v_cvt_pk_bf16_f32 v124, v124, v125
	v_cvt_pk_bf16_f32 v125, v112, v113
	v_add_f32_dpp v112, v152, v152 quad_perm:[1,0,3,2] row_mask:0xf bank_mask:0xf bound_ctrl:1
	v_add_f32_dpp v3, v3, v3 row_half_mirror row_mask:0xf bank_mask:0xf bound_ctrl:1
	global_store_dwordx2 v[146:147], v[124:125], off sc1
	v_add_f32_dpp v112, v112, v112 quad_perm:[2,3,0,1] row_mask:0xf bank_mask:0xf bound_ctrl:1
	v_add_f32_dpp v3, v3, v3 row_mirror row_mask:0xf bank_mask:0xf bound_ctrl:1
	v_add_f32_dpp v113, v150, v150 quad_perm:[1,0,3,2] row_mask:0xf bank_mask:0xf bound_ctrl:1
	v_add_f32_dpp v112, v112, v112 row_half_mirror row_mask:0xf bank_mask:0xf bound_ctrl:1
	v_mov_b32_e32 v125, v3
	v_add_f32_e32 v136, v136, v137
	v_add_f32_dpp v113, v113, v113 quad_perm:[2,3,0,1] row_mask:0xf bank_mask:0xf bound_ctrl:1
	v_add_f32_dpp v112, v112, v112 row_mirror row_mask:0xf bank_mask:0xf bound_ctrl:1
	v_permlane16_swap_b32_e32 v3, v125
	v_add_f32_dpp v124, v136, v136 quad_perm:[1,0,3,2] row_mask:0xf bank_mask:0xf bound_ctrl:1
	v_add_f32_dpp v113, v113, v113 row_half_mirror row_mask:0xf bank_mask:0xf bound_ctrl:1
	v_add_f32_e32 v3, v3, v125
	v_mov_b32_e32 v125, v112
	v_add_f32_dpp v124, v124, v124 quad_perm:[2,3,0,1] row_mask:0xf bank_mask:0xf bound_ctrl:1
	v_add_f32_dpp v113, v113, v113 row_mirror row_mask:0xf bank_mask:0xf bound_ctrl:1
	v_permlane16_swap_b32_e32 v112, v125
	v_add_f32_dpp v124, v124, v124 row_half_mirror row_mask:0xf bank_mask:0xf bound_ctrl:1
	v_add_f32_e32 v112, v112, v125
	v_mov_b32_e32 v125, v113
	v_add_f32_dpp v124, v124, v124 row_mirror row_mask:0xf bank_mask:0xf bound_ctrl:1
	s_nop 0
	v_permlane16_swap_b32_e32 v113, v125
	v_add_f32_e32 v113, v113, v125
	v_mov_b32_e32 v125, v124
	s_nop 1
	v_permlane16_swap_b32_e32 v124, v125
	v_add_f32_e32 v125, v124, v125
	v_mov_b32_e32 v124, v3
	v_mov_b32_e32 v136, v112
	v_mov_b32_e32 v137, v113
	v_mov_b32_e32 v144, v125
	v_permlane32_swap_b32_e32 v3, v124
	v_permlane32_swap_b32_e32 v112, v136
	v_permlane32_swap_b32_e32 v113, v137
	v_permlane32_swap_b32_e32 v125, v144
	s_and_saveexec_b64 s[10:11], s[38:39]
	s_cbranch_execz .LBB0_1070
	v_add_f32_e32 v146, v160, v164
	v_add_f32_e32 v160, v190, v193
	v_add_f32_e32 v147, v159, v163
	v_add_f32_e32 v159, v191, v195
	v_cndmask_b32_e64 v160, 0, v160, s[40:41]
	v_add_f32_e32 v148, v158, v161
	v_add_f32_e32 v158, v192, v196
	v_cndmask_b32_e32 v159, v160, v159, vcc
	v_add_f32_e32 v153, v194, v197
	v_cndmask_b32_e64 v158, v159, v158, s[42:43]
	v_add_f32_e32 v152, v174, v177
	v_cndmask_b32_e64 v153, v158, v153, s[44:45]
	v_add_f32_e32 v151, v175, v179
	v_cndmask_b32_e64 v152, v153, v152, s[46:47]
	v_add_f32_e32 v150, v176, v180
	v_cndmask_b32_e64 v151, v152, v151, s[48:49]
	v_add_f32_e32 v149, v178, v181
	v_cndmask_b32_e64 v150, v151, v150, s[50:51]
	v_cndmask_b32_e64 v149, v150, v149, s[52:53]
	v_cndmask_b32_e64 v148, v149, v148, s[54:55]
	v_cndmask_b32_e64 v147, v148, v147, s[56:57]
	v_add_f32_e32 v145, v162, v165
	v_cndmask_b32_e64 v146, v147, v146, s[58:59]
	v_cndmask_b32_e64 v145, v146, v145, s[60:61]
	v_add_f32_e32 v3, v3, v124
	v_cmp_eq_u32_e64 s[4:5], 12, v216
	v_add_f32_e32 v112, v112, v136
	v_add_f32_e32 v113, v113, v137
	v_cndmask_b32_e64 v3, v145, v3, s[4:5]
	v_cmp_eq_u32_e64 s[4:5], 13, v216
	v_add_f32_e32 v125, v125, v144
	s_nop 0
	v_cndmask_b32_e64 v3, v3, v112, s[4:5]
	v_cmp_eq_u32_e64 s[4:5], 14, v216
	s_nop 1
	v_cndmask_b32_e64 v3, v3, v113, s[4:5]
	v_cmp_eq_u32_e64 s[4:5], 15, v216
	s_nop 1
	v_cndmask_b32_e64 v124, v3, v125, s[4:5]
	v_ashrrev_i32_e32 v3, 31, v2
	v_lshlrev_b64 v[112:113], 5, v[2:3]
	v_lshl_add_u64 v[112:113], s[8:9], 0, v[112:113]
	v_lshl_add_u64 v[112:113], s[6:7], 2, v[112:113]
	global_store_dword v[112:113], v124, off
; #define LAS __attribute__((address_space(3)))
;     __device__ __forceinline__ HT hload(unsigned eoff) const { const u32x2 a = *(const u32x2*)((const char*)hi + eoff * 2u); const u32x2 b = *(const u32x2*)((const char*)lo + eoff * 2u); return (u32x4){a.x, a.y, b.x, b.y}; }
;     __device__ __forceinline__ void fused(f32x4 (&acc)[2][2][4][2], const Unit& u, int wr, int wc, int fr, int fq, LAS unsigned char* lds, int wid, int lane) const {
;     ...
;             if (ai == 1) {
; #pragma unroll
;             for (int m = 0; m < 4; ++m)
; #pragma unroll
;                 for (int bj = 0; bj < 2; ++bj)
; #pragma unroll
;                     for (int n = 0; n < 2; ++n) { const int r = wr * 64 + m * 16 + fr, c16 = 32 * bj + 8 * wc + 4 * n + fq;
;                         *(LAS f32x4*)(lds + r * 1024 + ((c16 ^ (r & 15)) << 4)) = acc[1][bj][m][n]; }
;             }
;             asm volatile("s_waitcnt lgkmcnt(0)" ::: "memory"); __builtin_amdgcn_s_barrier(); asm volatile("" ::: "memory");
;             if (ai == 0) {
;                 asm volatile("" :: "v"(H[0]), "v"(H[1]), "v"(H[2]), "v"(H[3]), "v"(H[4]), "v"(H[5]), "v"(H[6]), "v"(H[7]), "v"(H[8]), "v"(H[9]), "v"(H[10]), "v"(H[11]), "v"(H[12]), "v"(H[13]), "v"(H[14]), "v"(H[15]));
; #pragma unroll
;                 for (int j = 0; j < 16; ++j) H2[j] = hload(rbase + (unsigned)((HALF + j) * D));
;             }
;             float sqt = 0.f;
;     ...
;             if (ai == 0) EN_ROWS(4); else EN_ROWS(8);
.LBB0_1070:
	s_or_b64 exec, exec, s[10:11]
	s_waitcnt lgkmcnt(0)
	s_barrier
	ds_write_b128 v217, v[66:69]
	ds_write_b128 v218, v[62:65]
	ds_write_b128 v219, v[46:49]
	ds_write_b128 v220, v[38:41]
	ds_write_b128 v217, v[58:61] offset:16384
	ds_write_b128 v218, v[54:57] offset:16384
	ds_write_b128 v219, v[30:33] offset:16384
	ds_write_b128 v220, v[22:25] offset:16384
	ds_write_b128 v217, v[50:53] offset:32768
	ds_write_b128 v218, v[42:45] offset:32768
	ds_write_b128 v219, v[18:21] offset:32768
	ds_write_b128 v220, v[14:17] offset:32768
	ds_write_b128 v217, v[34:37] offset:49152
	ds_write_b128 v218, v[26:29] offset:49152
	ds_write_b128 v219, v[10:13] offset:49152
	ds_write_b128 v220, v[6:9] offset:49152
	s_waitcnt lgkmcnt(0)
	s_barrier
	v_mov_b32_e32 v3, s12
	ds_read_b128 v[6:9], v4
	ds_read_b128 v[10:13], v221
	ds_read_b128 v[14:17], v222
	ds_read_b128 v[18:21], v223
	v_mov_b32_e32 v4, s15
	ds_read_b128 v[22:25], v3 offset:512
	ds_read_b128 v[26:29], v4 offset:512
	ds_read_b128 v[30:33], v186
	ds_read_b128 v[34:37], v187
	ds_read_b128 v[38:41], v188
	ds_read_b128 v[42:45], v189
	s_waitcnt vmcnt(31)
	v_lshlrev_b32_e32 v46, 16, v142
	v_and_b32_e32 v47, 0xffff0000, v142
	s_waitcnt lgkmcnt(9)
	v_pk_mul_f32 v[6:7], v[70:71], v[6:7]
	v_lshlrev_b32_e32 v48, 16, v143
	v_and_b32_e32 v49, 0xffff0000, v143
	v_pk_mul_f32 v[8:9], v[72:73], v[8:9]
	s_waitcnt lgkmcnt(5)
	v_pk_fma_f32 v[6:7], v[6:7], v[22:23], v[46:47] op_sel_hi:[1,0,1]
	v_pk_fma_f32 v[8:9], v[8:9], v[22:23], v[48:49] op_sel_hi:[1,0,1]
	v_mul_f32_e32 v3, v7, v7
	v_fmac_f32_e32 v3, v6, v6
	v_mul_f32_e32 v4, v9, v9
	v_cvt_pk_bf16_f32 v6, v6, v7
	v_cvt_pk_bf16_f32 v7, v8, v9
	v_fmac_f32_e32 v4, v8, v8
	global_store_dwordx2 v[134:135], v[6:7], off sc1
	s_waitcnt vmcnt(31)
	v_lshlrev_b32_e32 v6, 16, v138
	v_and_b32_e32 v7, 0xffff0000, v138
	v_lshlrev_b32_e32 v8, 16, v139
	v_and_b32_e32 v9, 0xffff0000, v139
	v_pk_mul_f32 v[12:13], v[72:73], v[12:13]
	v_pk_mul_f32 v[10:11], v[70:71], v[10:11]
	v_pk_fma_f32 v[8:9], v[12:13], v[22:23], v[8:9] op_sel:[0,1,0]
	v_pk_fma_f32 v[6:7], v[10:11], v[22:23], v[6:7] op_sel:[0,1,0]
	v_add_f32_e32 v3, v3, v4
	v_mul_f32_e32 v4, v7, v7
	v_mul_f32_e32 v10, v9, v9
	v_fmac_f32_e32 v4, v6, v6
	v_fmac_f32_e32 v10, v8, v8
	v_cvt_pk_bf16_f32 v6, v6, v7
	v_cvt_pk_bf16_f32 v7, v8, v9
	v_add_f32_e32 v22, v4, v10
	global_store_dwordx2 v[130:131], v[6:7], off sc1
	s_waitcnt vmcnt(31)
	v_lshlrev_b32_e32 v6, 16, v140
	v_and_b32_e32 v7, 0xffff0000, v140
	v_lshlrev_b32_e32 v8, 16, v141
	v_and_b32_e32 v9, 0xffff0000, v141
	v_pk_mul_f32 v[10:11], v[72:73], v[16:17]
	v_pk_mul_f32 v[12:13], v[70:71], v[14:15]
	v_pk_fma_f32 v[8:9], v[10:11], v[24:25], v[8:9] op_sel_hi:[1,0,1]
	v_pk_fma_f32 v[6:7], v[12:13], v[24:25], v[6:7] op_sel_hi:[1,0,1]
	v_mul_f32_e32 v10, v9, v9
	v_mul_f32_e32 v4, v7, v7
	v_fmac_f32_e32 v4, v6, v6
	v_fmac_f32_e32 v10, v8, v8
	v_cvt_pk_bf16_f32 v6, v6, v7
	v_cvt_pk_bf16_f32 v7, v8, v9
	v_add_f32_e32 v14, v4, v10
	global_store_dwordx2 v[122:123], v[6:7], off sc1
	s_waitcnt vmcnt(31)
	v_lshlrev_b32_e32 v6, 16, v132
	v_and_b32_e32 v7, 0xffff0000, v132
	v_lshlrev_b32_e32 v8, 16, v133
	v_and_b32_e32 v9, 0xffff0000, v133
	v_pk_mul_f32 v[10:11], v[72:73], v[20:21]
	v_pk_mul_f32 v[12:13], v[70:71], v[18:19]
	v_mov_b32_e32 v4, v25
	v_pk_fma_f32 v[8:9], v[10:11], v[4:5], v[8:9] op_sel_hi:[1,0,1]
	v_pk_fma_f32 v[6:7], v[12:13], v[4:5], v[6:7] op_sel_hi:[1,0,1]
	v_mul_f32_e32 v10, v9, v9
	v_mul_f32_e32 v4, v7, v7
	v_fmac_f32_e32 v4, v6, v6
	v_fmac_f32_e32 v10, v8, v8
	v_cvt_pk_bf16_f32 v6, v6, v7
	v_cvt_pk_bf16_f32 v7, v8, v9
	v_add_f32_e32 v15, v4, v10
	global_store_dwordx2 v[118:119], v[6:7], off sc1
	s_waitcnt vmcnt(31)
	v_lshlrev_b32_e32 v6, 16, v128
	v_and_b32_e32 v7, 0xffff0000, v128
	v_lshlrev_b32_e32 v8, 16, v129
	v_and_b32_e32 v9, 0xffff0000, v129
	s_waitcnt lgkmcnt(3)
	v_pk_mul_f32 v[10:11], v[72:73], v[32:33]
	v_pk_mul_f32 v[12:13], v[70:71], v[30:31]
	v_pk_fma_f32 v[8:9], v[10:11], v[26:27], v[8:9] op_sel_hi:[1,0,1]
	v_pk_fma_f32 v[6:7], v[12:13], v[26:27], v[6:7] op_sel_hi:[1,0,1]
	v_mul_f32_e32 v10, v9, v9
	v_mul_f32_e32 v4, v7, v7
	v_fmac_f32_e32 v4, v6, v6
	v_fmac_f32_e32 v10, v8, v8
	v_cvt_pk_bf16_f32 v6, v6, v7
	v_cvt_pk_bf16_f32 v7, v8, v9
	v_add_f32_e32 v16, v4, v10
	global_store_dwordx2 v[116:117], v[6:7], off sc1
	s_waitcnt vmcnt(31)
	v_lshlrev_b32_e32 v6, 16, v120
	v_and_b32_e32 v7, 0xffff0000, v120
	v_lshlrev_b32_e32 v8, 16, v121
	v_and_b32_e32 v9, 0xffff0000, v121
	s_waitcnt lgkmcnt(2)
	v_pk_mul_f32 v[10:11], v[72:73], v[36:37]
	v_pk_mul_f32 v[12:13], v[70:71], v[34:35]
	v_pk_fma_f32 v[8:9], v[10:11], v[26:27], v[8:9] op_sel:[0,1,0]
	v_pk_fma_f32 v[6:7], v[12:13], v[26:27], v[6:7] op_sel:[0,1,0]
	v_mul_f32_e32 v10, v9, v9
	v_mul_f32_e32 v4, v7, v7
	v_fmac_f32_e32 v4, v6, v6
	v_fmac_f32_e32 v10, v8, v8
	v_cvt_pk_bf16_f32 v6, v6, v7
	v_cvt_pk_bf16_f32 v7, v8, v9
	v_add_f32_e32 v17, v4, v10
	global_store_dwordx2 v[110:111], v[6:7], off sc1
	s_waitcnt vmcnt(31)
	v_lshlrev_b32_e32 v6, 16, v126
	v_and_b32_e32 v7, 0xffff0000, v126
	v_lshlrev_b32_e32 v8, 16, v127
	v_and_b32_e32 v9, 0xffff0000, v127
	s_waitcnt lgkmcnt(1)
	v_pk_mul_f32 v[10:11], v[72:73], v[40:41]
	v_pk_mul_f32 v[12:13], v[70:71], v[38:39]
	v_pk_fma_f32 v[8:9], v[10:11], v[28:29], v[8:9] op_sel_hi:[1,0,1]
	v_pk_fma_f32 v[6:7], v[12:13], v[28:29], v[6:7] op_sel_hi:[1,0,1]
	v_mul_f32_e32 v10, v9, v9
	v_mul_f32_e32 v4, v7, v7
	v_fmac_f32_e32 v4, v6, v6
	v_fmac_f32_e32 v10, v8, v8
	v_cvt_pk_bf16_f32 v6, v6, v7
	v_cvt_pk_bf16_f32 v7, v8, v9
	v_add_f32_e32 v18, v4, v10
	global_store_dwordx2 v[108:109], v[6:7], off sc1
	s_waitcnt vmcnt(31)
;     __device__ __forceinline__ void fused(f32x4 (&acc)[2][2][4][2], const Unit& u, int wr, int wc, int fr, int fq, LAS unsigned char* lds, int wid, int lane) const {
;     ...
;             if (ai == 0) EN_ROWS(4); else EN_ROWS(8);
	v_lshlrev_b32_e32 v6, 16, v114
	v_and_b32_e32 v7, 0xffff0000, v114
	v_lshlrev_b32_e32 v8, 16, v115
	v_and_b32_e32 v9, 0xffff0000, v115
	s_waitcnt lgkmcnt(0)
	v_pk_mul_f32 v[10:11], v[72:73], v[44:45]
	v_pk_mul_f32 v[12:13], v[70:71], v[42:43]
	v_mov_b32_e32 v4, v29
	v_pk_fma_f32 v[8:9], v[10:11], v[4:5], v[8:9] op_sel_hi:[1,0,1]
	v_pk_fma_f32 v[6:7], v[12:13], v[4:5], v[6:7] op_sel_hi:[1,0,1]
	v_mul_f32_e32 v10, v9, v9
	v_mul_f32_e32 v4, v7, v7
	v_fmac_f32_e32 v4, v6, v6
	v_fmac_f32_e32 v10, v8, v8
	v_add_f32_e32 v4, v4, v10
	v_add_f32_dpp v3, v3, v3 quad_perm:[1,0,3,2] row_mask:0xf bank_mask:0xf bound_ctrl:1
	v_cvt_pk_bf16_f32 v6, v6, v7
	v_cvt_pk_bf16_f32 v7, v8, v9
	v_add_f32_dpp v4, v4, v4 quad_perm:[1,0,3,2] row_mask:0xf bank_mask:0xf bound_ctrl:1
	v_add_f32_dpp v3, v3, v3 quad_perm:[2,3,0,1] row_mask:0xf bank_mask:0xf bound_ctrl:1
	global_store_dwordx2 v[106:107], v[6:7], off sc1
	v_add_f32_dpp v6, v22, v22 quad_perm:[1,0,3,2] row_mask:0xf bank_mask:0xf bound_ctrl:1
	v_add_f32_dpp v4, v4, v4 quad_perm:[2,3,0,1] row_mask:0xf bank_mask:0xf bound_ctrl:1
	v_add_f32_dpp v3, v3, v3 row_half_mirror row_mask:0xf bank_mask:0xf bound_ctrl:1
	v_add_f32_dpp v6, v6, v6 quad_perm:[2,3,0,1] row_mask:0xf bank_mask:0xf bound_ctrl:1
	v_add_f32_dpp v4, v4, v4 row_half_mirror row_mask:0xf bank_mask:0xf bound_ctrl:1
	v_add_f32_dpp v3, v3, v3 row_mirror row_mask:0xf bank_mask:0xf bound_ctrl:1
	v_add_f32_dpp v7, v14, v14 quad_perm:[1,0,3,2] row_mask:0xf bank_mask:0xf bound_ctrl:1
	v_add_f32_dpp v6, v6, v6 row_half_mirror row_mask:0xf bank_mask:0xf bound_ctrl:1
	v_add_f32_dpp v12, v4, v4 row_mirror row_mask:0xf bank_mask:0xf bound_ctrl:1
	v_mov_b32_e32 v4, v3
	v_add_f32_dpp v7, v7, v7 quad_perm:[2,3,0,1] row_mask:0xf bank_mask:0xf bound_ctrl:1
	v_add_f32_dpp v6, v6, v6 row_mirror row_mask:0xf bank_mask:0xf bound_ctrl:1
	v_permlane16_swap_b32_e32 v3, v4
	v_add_f32_dpp v8, v15, v15 quad_perm:[1,0,3,2] row_mask:0xf bank_mask:0xf bound_ctrl:1
	v_add_f32_dpp v7, v7, v7 row_half_mirror row_mask:0xf bank_mask:0xf bound_ctrl:1
	v_add_f32_e32 v3, v3, v4
	v_mov_b32_e32 v4, v6
	v_add_f32_dpp v8, v8, v8 quad_perm:[2,3,0,1] row_mask:0xf bank_mask:0xf bound_ctrl:1
	v_add_f32_dpp v7, v7, v7 row_mirror row_mask:0xf bank_mask:0xf bound_ctrl:1
	v_permlane16_swap_b32_e32 v6, v4
	v_add_f32_dpp v9, v16, v16 quad_perm:[1,0,3,2] row_mask:0xf bank_mask:0xf bound_ctrl:1
	v_add_f32_dpp v8, v8, v8 row_half_mirror row_mask:0xf bank_mask:0xf bound_ctrl:1
	v_add_f32_e32 v4, v6, v4
	v_mov_b32_e32 v6, v7
	v_add_f32_dpp v9, v9, v9 quad_perm:[2,3,0,1] row_mask:0xf bank_mask:0xf bound_ctrl:1
	v_add_f32_dpp v8, v8, v8 row_mirror row_mask:0xf bank_mask:0xf bound_ctrl:1
	v_permlane16_swap_b32_e32 v7, v6
	v_add_f32_dpp v10, v17, v17 quad_perm:[1,0,3,2] row_mask:0xf bank_mask:0xf bound_ctrl:1
	v_add_f32_dpp v9, v9, v9 row_half_mirror row_mask:0xf bank_mask:0xf bound_ctrl:1
	v_add_f32_e32 v6, v7, v6
	v_mov_b32_e32 v7, v8
	v_add_f32_dpp v10, v10, v10 quad_perm:[2,3,0,1] row_mask:0xf bank_mask:0xf bound_ctrl:1
	v_add_f32_dpp v9, v9, v9 row_mirror row_mask:0xf bank_mask:0xf bound_ctrl:1
	v_permlane16_swap_b32_e32 v8, v7
	v_add_f32_dpp v11, v18, v18 quad_perm:[1,0,3,2] row_mask:0xf bank_mask:0xf bound_ctrl:1
	v_add_f32_dpp v10, v10, v10 row_half_mirror row_mask:0xf bank_mask:0xf bound_ctrl:1
	v_add_f32_e32 v7, v8, v7
	v_mov_b32_e32 v8, v9
	v_add_f32_dpp v11, v11, v11 quad_perm:[2,3,0,1] row_mask:0xf bank_mask:0xf bound_ctrl:1
	v_add_f32_dpp v10, v10, v10 row_mirror row_mask:0xf bank_mask:0xf bound_ctrl:1
	v_permlane16_swap_b32_e32 v9, v8
	v_mov_b32_e32 v19, s13
	v_mov_b32_e32 v40, s14
	v_add_f32_dpp v11, v11, v11 row_half_mirror row_mask:0xf bank_mask:0xf bound_ctrl:1
	v_add_f32_e32 v8, v9, v8
	v_mov_b32_e32 v9, v10
	ds_read_b128 v[20:23], v170
	ds_read_b128 v[24:27], v171
	ds_read_b128 v[28:31], v172
	ds_read_b128 v[32:35], v173
	ds_read_b128 v[36:39], v19 offset:512
	ds_read_b128 v[40:43], v40 offset:512
	ds_read_b128 v[44:47], v154
	ds_read_b128 v[48:51], v155
	ds_read_b128 v[52:55], v156
	ds_read_b128 v[56:59], v157
	v_add_f32_dpp v11, v11, v11 row_mirror row_mask:0xf bank_mask:0xf bound_ctrl:1
	v_permlane16_swap_b32_e32 v10, v9
	v_add_f32_e32 v9, v10, v9
	v_mov_b32_e32 v10, v11
	s_nop 1
	v_permlane16_swap_b32_e32 v11, v10
	v_add_f32_e32 v11, v11, v10
	v_mov_b32_e32 v10, v12
	s_nop 1
	v_permlane16_swap_b32_e32 v12, v10
	v_add_f32_e32 v13, v12, v10
	v_mov_b32_e32 v10, v3
	v_mov_b32_e32 v12, v4
	v_mov_b32_e32 v14, v6
	v_mov_b32_e32 v15, v7
	v_mov_b32_e32 v16, v8
	v_mov_b32_e32 v17, v9
	v_mov_b32_e32 v18, v11
	v_mov_b32_e32 v19, v13
	v_permlane32_swap_b32_e32 v3, v10
	v_permlane32_swap_b32_e32 v4, v12
	v_permlane32_swap_b32_e32 v6, v14
	v_permlane32_swap_b32_e32 v7, v15
	v_permlane32_swap_b32_e32 v8, v16
	v_permlane32_swap_b32_e32 v9, v17
	v_permlane32_swap_b32_e32 v11, v18
	v_permlane32_swap_b32_e32 v13, v19
	s_waitcnt vmcnt(31)
	v_lshlrev_b32_e32 v60, 16, v104
	v_and_b32_e32 v61, 0xffff0000, v104
	s_waitcnt lgkmcnt(9)
	v_pk_mul_f32 v[20:21], v[70:71], v[20:21]
	v_lshlrev_b32_e32 v62, 16, v105
	v_and_b32_e32 v63, 0xffff0000, v105
	v_pk_mul_f32 v[22:23], v[72:73], v[22:23]
	s_waitcnt lgkmcnt(5)
	v_pk_fma_f32 v[20:21], v[20:21], v[36:37], v[60:61] op_sel_hi:[1,0,1]
	v_pk_fma_f32 v[22:23], v[22:23], v[36:37], v[62:63] op_sel_hi:[1,0,1]
	v_mul_f32_e32 v60, v21, v21
	v_fmac_f32_e32 v60, v20, v20
	v_mul_f32_e32 v61, v23, v23
	v_cvt_pk_bf16_f32 v20, v20, v21
	v_cvt_pk_bf16_f32 v21, v22, v23
	v_fmac_f32_e32 v61, v22, v22
	global_store_dwordx2 v[98:99], v[20:21], off sc1
	s_waitcnt vmcnt(31)
;     __device__ __forceinline__ void fused(f32x4 (&acc)[2][2][4][2], const Unit& u, int wr, int wc, int fr, int fq, LAS unsigned char* lds, int wid, int lane) const {
;     ...
;             if (ai == 0) EN_ROWS(4); else EN_ROWS(8);
	v_lshlrev_b32_e32 v20, 16, v100
	v_and_b32_e32 v21, 0xffff0000, v100
	v_lshlrev_b32_e32 v22, 16, v101
	v_and_b32_e32 v23, 0xffff0000, v101
	v_pk_mul_f32 v[26:27], v[72:73], v[26:27]
	v_pk_mul_f32 v[24:25], v[70:71], v[24:25]
	v_pk_fma_f32 v[22:23], v[26:27], v[36:37], v[22:23] op_sel:[0,1,0]
	v_pk_fma_f32 v[20:21], v[24:25], v[36:37], v[20:21] op_sel:[0,1,0]
	v_mul_f32_e32 v25, v23, v23
	v_mul_f32_e32 v24, v21, v21
	v_fmac_f32_e32 v24, v20, v20
	v_fmac_f32_e32 v25, v22, v22
	v_cvt_pk_bf16_f32 v20, v20, v21
	v_cvt_pk_bf16_f32 v21, v22, v23
	v_add_f32_e32 v36, v24, v25
	global_store_dwordx2 v[94:95], v[20:21], off sc1
	s_waitcnt vmcnt(31)
	v_lshlrev_b32_e32 v20, 16, v102
	v_and_b32_e32 v21, 0xffff0000, v102
	v_lshlrev_b32_e32 v22, 16, v103
	v_and_b32_e32 v23, 0xffff0000, v103
	v_pk_mul_f32 v[24:25], v[72:73], v[30:31]
	v_pk_mul_f32 v[26:27], v[70:71], v[28:29]
	v_pk_fma_f32 v[22:23], v[24:25], v[38:39], v[22:23] op_sel_hi:[1,0,1]
	v_pk_fma_f32 v[20:21], v[26:27], v[38:39], v[20:21] op_sel_hi:[1,0,1]
	v_mul_f32_e32 v25, v23, v23
	v_mul_f32_e32 v24, v21, v21
	v_fmac_f32_e32 v24, v20, v20
	v_fmac_f32_e32 v25, v22, v22
	v_cvt_pk_bf16_f32 v20, v20, v21
	v_cvt_pk_bf16_f32 v21, v22, v23
	v_add_f32_e32 v29, v24, v25
	global_store_dwordx2 v[88:89], v[20:21], off sc1
	s_waitcnt vmcnt(31)
	v_lshlrev_b32_e32 v20, 16, v96
	v_and_b32_e32 v21, 0xffff0000, v96
	v_lshlrev_b32_e32 v22, 16, v97
	v_and_b32_e32 v23, 0xffff0000, v97
	v_pk_mul_f32 v[24:25], v[72:73], v[34:35]
	v_pk_mul_f32 v[26:27], v[70:71], v[32:33]
	v_mov_b32_e32 v28, v39
	v_pk_fma_f32 v[22:23], v[24:25], v[28:29], v[22:23] op_sel_hi:[1,0,1]
	v_pk_fma_f32 v[20:21], v[26:27], v[28:29], v[20:21] op_sel_hi:[1,0,1]
	v_mul_f32_e32 v25, v23, v23
	v_mul_f32_e32 v24, v21, v21
	v_fmac_f32_e32 v24, v20, v20
	v_fmac_f32_e32 v25, v22, v22
	v_cvt_pk_bf16_f32 v20, v20, v21
	v_cvt_pk_bf16_f32 v21, v22, v23
	v_add_f32_e32 v30, v24, v25
	global_store_dwordx2 v[84:85], v[20:21], off sc1
	s_waitcnt vmcnt(31)
	v_lshlrev_b32_e32 v20, 16, v92
	v_and_b32_e32 v21, 0xffff0000, v92
	v_lshlrev_b32_e32 v22, 16, v93
	v_and_b32_e32 v23, 0xffff0000, v93
	s_waitcnt lgkmcnt(3)
	v_pk_mul_f32 v[24:25], v[72:73], v[46:47]
	v_pk_mul_f32 v[26:27], v[70:71], v[44:45]
	v_pk_fma_f32 v[22:23], v[24:25], v[40:41], v[22:23] op_sel_hi:[1,0,1]
	v_pk_fma_f32 v[20:21], v[26:27], v[40:41], v[20:21] op_sel_hi:[1,0,1]
	v_mul_f32_e32 v25, v23, v23
	v_mul_f32_e32 v24, v21, v21
	v_fmac_f32_e32 v24, v20, v20
	v_fmac_f32_e32 v25, v22, v22
	v_cvt_pk_bf16_f32 v20, v20, v21
	v_cvt_pk_bf16_f32 v21, v22, v23
	v_add_f32_e32 v31, v24, v25
	global_store_dwordx2 v[80:81], v[20:21], off sc1
	s_waitcnt vmcnt(31)
	v_lshlrev_b32_e32 v20, 16, v86
	v_and_b32_e32 v21, 0xffff0000, v86
	v_lshlrev_b32_e32 v22, 16, v87
	v_and_b32_e32 v23, 0xffff0000, v87
	s_waitcnt lgkmcnt(2)
	v_pk_mul_f32 v[24:25], v[72:73], v[50:51]
	v_pk_mul_f32 v[26:27], v[70:71], v[48:49]
	v_pk_fma_f32 v[22:23], v[24:25], v[40:41], v[22:23] op_sel:[0,1,0]
	v_pk_fma_f32 v[20:21], v[26:27], v[40:41], v[20:21] op_sel:[0,1,0]
	v_mul_f32_e32 v25, v23, v23
	v_mul_f32_e32 v24, v21, v21
	v_fmac_f32_e32 v24, v20, v20
	v_fmac_f32_e32 v25, v22, v22
	v_cvt_pk_bf16_f32 v20, v20, v21
	v_cvt_pk_bf16_f32 v21, v22, v23
	v_add_f32_e32 v32, v24, v25
	global_store_dwordx2 v[78:79], v[20:21], off sc1
	s_waitcnt vmcnt(31)
	v_lshlrev_b32_e32 v20, 16, v90
	v_and_b32_e32 v21, 0xffff0000, v90
	v_lshlrev_b32_e32 v22, 16, v91
	v_and_b32_e32 v23, 0xffff0000, v91
	s_waitcnt lgkmcnt(1)
	v_pk_mul_f32 v[24:25], v[72:73], v[54:55]
	v_pk_mul_f32 v[26:27], v[70:71], v[52:53]
	v_pk_fma_f32 v[22:23], v[24:25], v[42:43], v[22:23] op_sel_hi:[1,0,1]
	v_pk_fma_f32 v[20:21], v[26:27], v[42:43], v[20:21] op_sel_hi:[1,0,1]
	v_mul_f32_e32 v25, v23, v23
	v_mul_f32_e32 v24, v21, v21
	v_fmac_f32_e32 v24, v20, v20
	v_fmac_f32_e32 v25, v22, v22
	v_cvt_pk_bf16_f32 v20, v20, v21
	v_cvt_pk_bf16_f32 v21, v22, v23
	v_add_f32_e32 v33, v24, v25
	global_store_dwordx2 v[76:77], v[20:21], off sc1
	s_waitcnt vmcnt(31)
	v_lshlrev_b32_e32 v20, 16, v82
	v_and_b32_e32 v21, 0xffff0000, v82
	v_lshlrev_b32_e32 v22, 16, v83
	v_and_b32_e32 v23, 0xffff0000, v83
	s_waitcnt lgkmcnt(0)
;     __device__ __forceinline__ void fused(f32x4 (&acc)[2][2][4][2], const Unit& u, int wr, int wc, int fr, int fq, LAS unsigned char* lds, int wid, int lane) const {
;     ...
;             if (ai == 0) EN_ROWS(4); else EN_ROWS(8);
;     ...
;             if (lane < 16) st2[(size_t)(u.pm * BM + ai * HALF + 16 * wid + lane) * 8 + u.pn] = sqt;
	v_pk_mul_f32 v[24:25], v[72:73], v[58:59]
	v_pk_mul_f32 v[26:27], v[70:71], v[56:57]
	v_mov_b32_e32 v28, v43
	v_pk_fma_f32 v[22:23], v[24:25], v[28:29], v[22:23] op_sel_hi:[1,0,1]
	v_pk_fma_f32 v[20:21], v[26:27], v[28:29], v[20:21] op_sel_hi:[1,0,1]
	v_mul_f32_e32 v25, v23, v23
	v_mul_f32_e32 v24, v21, v21
	v_add_f32_e32 v60, v60, v61
	v_fmac_f32_e32 v24, v20, v20
	v_fmac_f32_e32 v25, v22, v22
	v_cvt_pk_bf16_f32 v20, v20, v21
	v_cvt_pk_bf16_f32 v21, v22, v23
	v_add_f32_e32 v24, v24, v25
	global_store_dwordx2 v[74:75], v[20:21], off sc1
	v_add_f32_dpp v20, v60, v60 quad_perm:[1,0,3,2] row_mask:0xf bank_mask:0xf bound_ctrl:1
	v_add_f32_dpp v24, v24, v24 quad_perm:[1,0,3,2] row_mask:0xf bank_mask:0xf bound_ctrl:1
	v_add_f32_dpp v21, v36, v36 quad_perm:[1,0,3,2] row_mask:0xf bank_mask:0xf bound_ctrl:1
	v_add_f32_dpp v20, v20, v20 quad_perm:[2,3,0,1] row_mask:0xf bank_mask:0xf bound_ctrl:1
	v_add_f32_dpp v24, v24, v24 quad_perm:[2,3,0,1] row_mask:0xf bank_mask:0xf bound_ctrl:1
	v_add_f32_dpp v21, v21, v21 quad_perm:[2,3,0,1] row_mask:0xf bank_mask:0xf bound_ctrl:1
	v_add_f32_dpp v20, v20, v20 row_half_mirror row_mask:0xf bank_mask:0xf bound_ctrl:1
	v_add_f32_dpp v24, v24, v24 row_half_mirror row_mask:0xf bank_mask:0xf bound_ctrl:1
	v_add_f32_dpp v22, v29, v29 quad_perm:[1,0,3,2] row_mask:0xf bank_mask:0xf bound_ctrl:1
	v_add_f32_dpp v20, v20, v20 row_mirror row_mask:0xf bank_mask:0xf bound_ctrl:1
	v_add_f32_dpp v21, v21, v21 row_half_mirror row_mask:0xf bank_mask:0xf bound_ctrl:1
	v_add_f32_dpp v28, v24, v24 row_mirror row_mask:0xf bank_mask:0xf bound_ctrl:1
	v_mov_b32_e32 v24, v20
	v_add_f32_dpp v22, v22, v22 quad_perm:[2,3,0,1] row_mask:0xf bank_mask:0xf bound_ctrl:1
	v_add_f32_dpp v21, v21, v21 row_mirror row_mask:0xf bank_mask:0xf bound_ctrl:1
	v_permlane16_swap_b32_e32 v20, v24
	v_add_f32_dpp v23, v30, v30 quad_perm:[1,0,3,2] row_mask:0xf bank_mask:0xf bound_ctrl:1
	v_add_f32_dpp v22, v22, v22 row_half_mirror row_mask:0xf bank_mask:0xf bound_ctrl:1
	v_add_f32_e32 v20, v20, v24
	v_mov_b32_e32 v24, v21
	v_add_f32_dpp v23, v23, v23 quad_perm:[2,3,0,1] row_mask:0xf bank_mask:0xf bound_ctrl:1
	v_add_f32_dpp v22, v22, v22 row_mirror row_mask:0xf bank_mask:0xf bound_ctrl:1
	v_permlane16_swap_b32_e32 v21, v24
	v_add_f32_dpp v25, v31, v31 quad_perm:[1,0,3,2] row_mask:0xf bank_mask:0xf bound_ctrl:1
	v_add_f32_dpp v23, v23, v23 row_half_mirror row_mask:0xf bank_mask:0xf bound_ctrl:1
	v_add_f32_e32 v21, v21, v24
	v_mov_b32_e32 v24, v22
	v_add_f32_dpp v25, v25, v25 quad_perm:[2,3,0,1] row_mask:0xf bank_mask:0xf bound_ctrl:1
	v_add_f32_dpp v23, v23, v23 row_mirror row_mask:0xf bank_mask:0xf bound_ctrl:1
	v_permlane16_swap_b32_e32 v22, v24
	v_add_f32_dpp v26, v32, v32 quad_perm:[1,0,3,2] row_mask:0xf bank_mask:0xf bound_ctrl:1
	v_add_f32_dpp v25, v25, v25 row_half_mirror row_mask:0xf bank_mask:0xf bound_ctrl:1
	v_add_f32_e32 v22, v22, v24
	v_mov_b32_e32 v24, v23
	v_add_f32_dpp v26, v26, v26 quad_perm:[2,3,0,1] row_mask:0xf bank_mask:0xf bound_ctrl:1
	v_add_f32_dpp v25, v25, v25 row_mirror row_mask:0xf bank_mask:0xf bound_ctrl:1
	v_permlane16_swap_b32_e32 v23, v24
	v_add_f32_dpp v27, v33, v33 quad_perm:[1,0,3,2] row_mask:0xf bank_mask:0xf bound_ctrl:1
	v_add_f32_dpp v26, v26, v26 row_half_mirror row_mask:0xf bank_mask:0xf bound_ctrl:1
	v_add_f32_e32 v23, v23, v24
	v_mov_b32_e32 v24, v25
	v_add_f32_dpp v27, v27, v27 quad_perm:[2,3,0,1] row_mask:0xf bank_mask:0xf bound_ctrl:1
	v_add_f32_dpp v26, v26, v26 row_mirror row_mask:0xf bank_mask:0xf bound_ctrl:1
	v_permlane16_swap_b32_e32 v25, v24
	v_add_f32_dpp v27, v27, v27 row_half_mirror row_mask:0xf bank_mask:0xf bound_ctrl:1
	v_add_f32_e32 v24, v25, v24
	v_mov_b32_e32 v25, v26
	v_add_f32_dpp v27, v27, v27 row_mirror row_mask:0xf bank_mask:0xf bound_ctrl:1
	s_nop 0
	v_permlane16_swap_b32_e32 v26, v25
	v_add_f32_e32 v25, v26, v25
	v_mov_b32_e32 v26, v27
	s_nop 1
	v_permlane16_swap_b32_e32 v27, v26
	v_add_f32_e32 v27, v27, v26
	v_mov_b32_e32 v26, v28
	s_nop 1
	v_permlane16_swap_b32_e32 v28, v26
	v_add_f32_e32 v30, v28, v26
	v_mov_b32_e32 v26, v20
	v_mov_b32_e32 v28, v21
	v_mov_b32_e32 v29, v22
	v_mov_b32_e32 v31, v23
	v_mov_b32_e32 v32, v24
	v_mov_b32_e32 v33, v25
	v_mov_b32_e32 v34, v27
	v_mov_b32_e32 v35, v30
	v_permlane32_swap_b32_e32 v20, v26
	v_permlane32_swap_b32_e32 v21, v28
	v_permlane32_swap_b32_e32 v22, v29
	v_permlane32_swap_b32_e32 v23, v31
	v_permlane32_swap_b32_e32 v24, v32
	v_permlane32_swap_b32_e32 v25, v33
	v_permlane32_swap_b32_e32 v27, v34
	v_permlane32_swap_b32_e32 v30, v35
	s_and_saveexec_b64 s[4:5], s[38:39]
	s_cbranch_execz .LBB0_1072
	v_add_f32_e32 v3, v3, v10
	v_add_f32_e32 v4, v4, v12
	v_cndmask_b32_e64 v3, 0, v3, s[40:41]
	v_add_f32_e32 v6, v6, v14
	v_cndmask_b32_e32 v3, v3, v4, vcc
	v_add_f32_e32 v7, v7, v15
	v_cndmask_b32_e64 v3, v3, v6, s[42:43]
	v_add_f32_e32 v8, v8, v16
	v_cndmask_b32_e64 v3, v3, v7, s[44:45]
	v_add_f32_e32 v9, v9, v17
	v_cndmask_b32_e64 v3, v3, v8, s[46:47]
	v_add_f32_e32 v11, v11, v18
	v_cndmask_b32_e64 v3, v3, v9, s[48:49]
	v_add_f32_e32 v13, v13, v19
	v_cndmask_b32_e64 v3, v3, v11, s[50:51]
	v_cndmask_b32_e64 v3, v3, v13, s[52:53]
	v_add_f32_e32 v12, v20, v26
	v_add_f32_e32 v11, v21, v28
	v_cndmask_b32_e64 v3, v3, v12, s[54:55]
	v_add_f32_e32 v10, v22, v29
	v_cndmask_b32_e64 v3, v3, v11, s[56:57]
	v_add_f32_e32 v9, v23, v31
	v_cndmask_b32_e64 v3, v3, v10, s[58:59]
	v_add_f32_e32 v8, v24, v32
	v_cndmask_b32_e64 v3, v3, v9, s[60:61]
	v_cmp_eq_u32_e32 vcc, 12, v216
	v_add_f32_e32 v7, v25, v33
	v_add_f32_e32 v6, v27, v34
	v_cndmask_b32_e32 v3, v3, v8, vcc
	v_cmp_eq_u32_e32 vcc, 13, v216
	v_add_f32_e32 v4, v30, v35
	v_add_u32_e32 v2, 0x80, v2
	v_cndmask_b32_e32 v3, v3, v7, vcc
	v_cmp_eq_u32_e32 vcc, 14, v216
	s_nop 1
	v_cndmask_b32_e32 v3, v3, v6, vcc
	v_cmp_eq_u32_e32 vcc, 15, v216
	s_nop 1
	v_cndmask_b32_e32 v4, v3, v4, vcc
	v_ashrrev_i32_e32 v3, 31, v2
	v_lshlrev_b64 v[2:3], 5, v[2:3]
	v_lshl_add_u64 v[2:3], s[8:9], 0, v[2:3]
	v_lshl_add_u64 v[2:3], s[6:7], 2, v[2:3]
	global_store_dword v[2:3], v4, off
